# RWKV pass 1: chunk-product matrix update moved from f32 MFMA to packed f32 VALU with LDS-broadcast operands
# speedup vs baseline: 1.2262x; 1.0031x over previous
; DI float bf2f(bf16_t b) { return __uint_as_float(((unsigned)b) << 16); }
; template <bool PASS2>
; DI void rwkv_item(const Params& p, int l, int item, int lane, const bf16_t* rkv, const bf16_t* lo2, float* rwst) {
;     ...
;   float S[64], P[64];
; #pragma unroll
;   for (int j = 0; j < 64; j++) { S[j] = 0.f; P[j] = (j == lane) ? 1.f : 0.f; }
;   if (PASS2 && c > 0) {
;     const float4* sp = (const float4*)(stS - 4096 + lane * 64);
; #pragma unroll
;     for (int j = 0; j < 16; j++) { float4 v = sp[j]; S[4 * j] = v.x; S[4 * j + 1] = v.y; S[4 * j + 2] = v.z; S[4 * j + 3] = v.w; }
;   }
;   float rp_prev = 0.f, kp_prev = 0.f;
;   if (c > 0) { rp_prev = bf2f(rkv[(tok0 - 1) * 1536 + ch]); kp_prev = bf2f(rkv[(tok0 - 1) * 1536 + 512 + ch]); }
;   const bf16_t* ewb = lo2; const bf16_t* ab = lo2 + (size_t)TOK * 512; const bf16_t* gb = lo2 + (size_t)2 * TOK * 512;
;   struct Raw { bf16_t rp, kp, v, ew, a, g; };
;   struct Der { float rr, wdec, kf, av, bv, v, gg; };
;   auto load_raw = [&](size_t tk) __attribute__((always_inline)) {
;     Raw x;
;     x.rp = rkv[tk * 1536 + ch]; x.kp = rkv[tk * 1536 + 512 + ch]; x.v = p.vbuf[tk * 512 + ch];
;     x.ew = ewb[tk * 512 + ch]; x.a = ab[tk * 512 + ch]; x.g = PASS2 ? gb[tk * 512 + ch] : (bf16_t)0;
;     return x;
.Lrwp1a_noprev:
	v_mov_b32_e32 v64, 0
	v_cmp_eq_u32_e64 s[28:29], 0, v27
	s_nop 1
	v_cndmask_b32_e64 v128, 0, 1.0, s[28:29]
	v_mov_b32_e32 v65, 0
	v_cmp_eq_u32_e64 s[28:29], 1, v27
	s_nop 1
	v_cndmask_b32_e64 v129, 0, 1.0, s[28:29]
	v_mov_b32_e32 v66, 0
	v_cmp_eq_u32_e64 s[28:29], 2, v27
	s_nop 1
	v_cndmask_b32_e64 v130, 0, 1.0, s[28:29]
	v_mov_b32_e32 v67, 0
	v_cmp_eq_u32_e64 s[28:29], 3, v27
	s_nop 1
	v_cndmask_b32_e64 v131, 0, 1.0, s[28:29]
	v_mov_b32_e32 v68, 0
	v_cmp_eq_u32_e64 s[28:29], 8, v27
	s_nop 1
	v_cndmask_b32_e64 v132, 0, 1.0, s[28:29]
	v_mov_b32_e32 v69, 0
	v_cmp_eq_u32_e64 s[28:29], 9, v27
	s_nop 1
	v_cndmask_b32_e64 v133, 0, 1.0, s[28:29]
	v_mov_b32_e32 v70, 0
	v_cmp_eq_u32_e64 s[28:29], 10, v27
	s_nop 1
	v_cndmask_b32_e64 v134, 0, 1.0, s[28:29]
	v_mov_b32_e32 v71, 0
	v_cmp_eq_u32_e64 s[28:29], 11, v27
	s_nop 1
	v_cndmask_b32_e64 v135, 0, 1.0, s[28:29]
	v_mov_b32_e32 v72, 0
	v_cmp_eq_u32_e64 s[28:29], 16, v27
	s_nop 1
	v_cndmask_b32_e64 v136, 0, 1.0, s[28:29]
	v_mov_b32_e32 v73, 0
	v_cmp_eq_u32_e64 s[28:29], 17, v27
	s_nop 1
	v_cndmask_b32_e64 v137, 0, 1.0, s[28:29]
	v_mov_b32_e32 v74, 0
	v_cmp_eq_u32_e64 s[28:29], 18, v27
	s_nop 1
	v_cndmask_b32_e64 v138, 0, 1.0, s[28:29]
	v_mov_b32_e32 v75, 0
	v_cmp_eq_u32_e64 s[28:29], 19, v27
	s_nop 1
	v_cndmask_b32_e64 v139, 0, 1.0, s[28:29]
	v_mov_b32_e32 v76, 0
	v_cmp_eq_u32_e64 s[28:29], 24, v27
	s_nop 1
	v_cndmask_b32_e64 v140, 0, 1.0, s[28:29]
	v_mov_b32_e32 v77, 0
	v_cmp_eq_u32_e64 s[28:29], 25, v27
	s_nop 1
	v_cndmask_b32_e64 v141, 0, 1.0, s[28:29]
	v_mov_b32_e32 v78, 0
	v_cmp_eq_u32_e64 s[28:29], 26, v27
	s_nop 1
	v_cndmask_b32_e64 v142, 0, 1.0, s[28:29]
	v_mov_b32_e32 v79, 0
	v_cmp_eq_u32_e64 s[28:29], 27, v27
	s_nop 1
	v_cndmask_b32_e64 v143, 0, 1.0, s[28:29]
	v_mov_b32_e32 v80, 0
	v_mov_b32_e32 v144, 0
	v_mov_b32_e32 v81, 0
	v_mov_b32_e32 v145, 0
	v_mov_b32_e32 v82, 0
	v_mov_b32_e32 v146, 0
	v_mov_b32_e32 v83, 0
	v_mov_b32_e32 v147, 0
	v_mov_b32_e32 v84, 0
	v_mov_b32_e32 v148, 0
	v_mov_b32_e32 v85, 0
	v_mov_b32_e32 v149, 0
	v_mov_b32_e32 v86, 0
	v_mov_b32_e32 v150, 0
	v_mov_b32_e32 v87, 0
	v_mov_b32_e32 v151, 0
	v_mov_b32_e32 v88, 0
	v_mov_b32_e32 v152, 0
	v_mov_b32_e32 v89, 0
	v_mov_b32_e32 v153, 0
	v_mov_b32_e32 v90, 0
	v_mov_b32_e32 v154, 0
	v_mov_b32_e32 v91, 0
	v_mov_b32_e32 v155, 0
	v_mov_b32_e32 v92, 0
	v_mov_b32_e32 v156, 0
	v_mov_b32_e32 v93, 0
	v_mov_b32_e32 v157, 0
	v_mov_b32_e32 v94, 0
	v_mov_b32_e32 v158, 0
	v_mov_b32_e32 v95, 0
	v_mov_b32_e32 v159, 0
	v_mov_b32_e32 v96, 0
	v_mov_b32_e32 v160, 0
	v_mov_b32_e32 v97, 0
	v_mov_b32_e32 v161, 0
	v_mov_b32_e32 v98, 0
	v_mov_b32_e32 v162, 0
	v_mov_b32_e32 v99, 0
	v_mov_b32_e32 v163, 0
	v_mov_b32_e32 v100, 0
	v_mov_b32_e32 v164, 0
	v_mov_b32_e32 v101, 0
	v_mov_b32_e32 v165, 0
	v_mov_b32_e32 v102, 0
	v_mov_b32_e32 v166, 0
	v_mov_b32_e32 v103, 0
	v_mov_b32_e32 v167, 0
	v_mov_b32_e32 v104, 0
	v_mov_b32_e32 v168, 0
	v_mov_b32_e32 v105, 0
	v_mov_b32_e32 v169, 0
	v_mov_b32_e32 v106, 0
	v_mov_b32_e32 v170, 0
	v_mov_b32_e32 v107, 0
	v_mov_b32_e32 v171, 0
	v_mov_b32_e32 v108, 0
	v_mov_b32_e32 v172, 0
	v_mov_b32_e32 v109, 0
	v_mov_b32_e32 v173, 0
	v_mov_b32_e32 v110, 0
	v_mov_b32_e32 v174, 0
	v_mov_b32_e32 v111, 0
	v_mov_b32_e32 v175, 0
	v_mov_b32_e32 v112, 0
	v_cmp_eq_u32_e64 s[28:29], 0, v27
	s_nop 1
	v_cndmask_b32_e64 v176, 0, 1.0, s[28:29]
	v_mov_b32_e32 v113, 0
	v_cmp_eq_u32_e64 s[28:29], 1, v27
	s_nop 1
	v_cndmask_b32_e64 v177, 0, 1.0, s[28:29]
	v_mov_b32_e32 v114, 0
	v_cmp_eq_u32_e64 s[28:29], 2, v27
	s_nop 1
	v_cndmask_b32_e64 v178, 0, 1.0, s[28:29]
	v_mov_b32_e32 v115, 0
	v_cmp_eq_u32_e64 s[28:29], 3, v27
	s_nop 1
	v_cndmask_b32_e64 v179, 0, 1.0, s[28:29]
	v_mov_b32_e32 v116, 0
	v_cmp_eq_u32_e64 s[28:29], 8, v27
	s_nop 1
	v_cndmask_b32_e64 v180, 0, 1.0, s[28:29]
	v_mov_b32_e32 v117, 0
	v_cmp_eq_u32_e64 s[28:29], 9, v27
	s_nop 1
	v_cndmask_b32_e64 v181, 0, 1.0, s[28:29]
	v_mov_b32_e32 v118, 0
	v_cmp_eq_u32_e64 s[28:29], 10, v27
	s_nop 1
	v_cndmask_b32_e64 v182, 0, 1.0, s[28:29]
	v_mov_b32_e32 v119, 0
	v_cmp_eq_u32_e64 s[28:29], 11, v27
	s_nop 1
	v_cndmask_b32_e64 v183, 0, 1.0, s[28:29]
	v_mov_b32_e32 v120, 0
	v_cmp_eq_u32_e64 s[28:29], 16, v27
	s_nop 1
	v_cndmask_b32_e64 v184, 0, 1.0, s[28:29]
	v_mov_b32_e32 v121, 0
	v_cmp_eq_u32_e64 s[28:29], 17, v27
	s_nop 1
	v_cndmask_b32_e64 v185, 0, 1.0, s[28:29]
	v_mov_b32_e32 v122, 0
	v_cmp_eq_u32_e64 s[28:29], 18, v27
	s_nop 1
	v_cndmask_b32_e64 v186, 0, 1.0, s[28:29]
	v_mov_b32_e32 v123, 0
	v_cmp_eq_u32_e64 s[28:29], 19, v27
	s_nop 1
	v_cndmask_b32_e64 v187, 0, 1.0, s[28:29]
	v_mov_b32_e32 v124, 0
	v_cmp_eq_u32_e64 s[28:29], 24, v27
	s_nop 1
	v_cndmask_b32_e64 v188, 0, 1.0, s[28:29]
	v_mov_b32_e32 v125, 0
	v_cmp_eq_u32_e64 s[28:29], 25, v27
	s_nop 1
	v_cndmask_b32_e64 v189, 0, 1.0, s[28:29]
	v_mov_b32_e32 v126, 0
	v_cmp_eq_u32_e64 s[28:29], 26, v27
	s_nop 1
	v_cndmask_b32_e64 v190, 0, 1.0, s[28:29]
	v_mov_b32_e32 v127, 0
	v_cmp_eq_u32_e64 s[28:29], 27, v27
	s_nop 1
	v_cndmask_b32_e64 v191, 0, 1.0, s[28:29]
	global_load_ushort v192, v3, s[4:5] offset:1024
	global_load_ushort v193, v4, s[6:7]
	global_load_ushort v194, v4, s[8:9]
	global_load_ushort v195, v4, s[10:11]
	v_add_u32_e32 v3, 0xc00, v3
	v_add_u32_e32 v4, 0x400, v4
	global_load_ushort v196, v3, s[4:5] offset:1024
	global_load_ushort v197, v4, s[6:7]
	global_load_ushort v198, v4, s[8:9]
	global_load_ushort v199, v4, s[10:11]
	v_add_u32_e32 v3, 0xc00, v3
	v_add_u32_e32 v4, 0x400, v4
	global_load_ushort v200, v3, s[4:5] offset:1024
	global_load_ushort v201, v4, s[6:7]
	global_load_ushort v202, v4, s[8:9]
	global_load_ushort v203, v4, s[10:11]
	v_add_u32_e32 v3, 0xc00, v3
	v_add_u32_e32 v4, 0x400, v4
	global_load_ushort v204, v3, s[4:5] offset:1024
	global_load_ushort v205, v4, s[6:7]
	global_load_ushort v206, v4, s[8:9]
	global_load_ushort v207, v4, s[10:11]
	v_add_u32_e32 v3, 0xc00, v3
	v_add_u32_e32 v4, 0x400, v4
	s_waitcnt vmcnt(0)
; DI float bf2f(bf16_t b) { return __uint_as_float(((unsigned)b) << 16); }
; DI float rl(float x, int l) { return __int_as_float(__builtin_amdgcn_readlane(__float_as_int(x), l)); }
; template <bool PASS2>
; DI void rwkv_item(const Params& p, int l, int item, int lane, const bf16_t* rkv, const bf16_t* lo2, float* rwst) {
;     ...
;   auto derive = [&](const Raw& x, float rpp, float kpp) __attribute__((always_inline)) {
;     Der d;
;     const float rp = bf2f(x.rp), kp = bf2f(x.kp), a = bf2f(x.a);
;     d.rr = rp + (rpp - rp) * mu_r;
;     const float k = kp + (kpp - kp) * mu_k;
;     d.wdec = __expf(-bf2f(x.ew));
;     float kkv = k * kkw;
;     const float nrm = wave_sum(kkv * kkv);
;     kkv *= rsqrtf(fmaxf(nrm, 1e-24f));
;     d.kf = k * (1.f + (a - 1.f) * kaw);
;     d.av = -kkv; d.bv = kkv * a;
;     d.v = bf2f(x.v); d.gg = bf2f(x.g);
;     return d;
;   };
;   Raw rawB = load_raw(tok0);
;   Der cur = derive(rawB, rp_prev, kp_prev);
;   float rpA = bf2f(rawB.rp), kpA = bf2f(rawB.kp);
;   rawB = load_raw(tok0 + 1);
; #pragma unroll 1
;   for (int t = 0; t < LCR; t++) {
;     Raw rawC = rawB;
;     if (t + 2 < LCR) rawC = load_raw(tok0 + t + 2);
;     Der nxt = cur;
;     if (t + 1 < LCR) nxt = derive(rawB, rpA, kpA);
;     const float rr = cur.rr, wdec = cur.wdec, kf = cur.kf, av = cur.av, bv = cur.bv, v = cur.v, gg = cur.gg;
;     float sa0 = 0.f, sa1 = 0.f, pa0 = 0.f, pa1 = 0.f;
; #pragma unroll
;     for (int j = 0; j < 64; j += 2) {
;       const float a0 = rl(av, j), a1 = rl(av, j + 1);
;       sa0 += S[j] * a0; sa1 += S[j + 1] * a1;
;       if (!PASS2) { pa0 += P[j] * a0; pa1 += P[j + 1] * a1; }
;     }
;     const float sa = sa0 + sa1, pa = pa0 + pa1;
	v_lshlrev_b32_e32 v6, 16, v6
	v_lshlrev_b32_e32 v7, 16, v7
	v_mov_b32_e32 v8, 1.0
	s_movk_i32 s36, 0x7fff
	v_lshlrev_b32_e32 v27, 16, v192
	v_sub_f32_e32 v29, v7, v27
	v_fma_f32 v29, v29, v10, v27
	v_mov_b32_e32 v7, v27
	v_lshlrev_b32_e32 v30, 16, v194
	v_mul_f32_e32 v30, 0xbfb8aa3b, v30
	v_exp_f32_e32 v30, v30
	v_lshlrev_b32_e32 v31, 16, v195
	v_mul_f32_e32 v211, v29, v11
	v_add_f32_e32 v212, -1.0, v31
	v_fma_f32 v212, v212, v12, 1.0
	v_mul_f32_e32 v212, v29, v212
	v_mul_f32_e32 v213, v211, v211
	v_mov_b32_e32 v214, 0
	v_lshlrev_b32_e32 v20, 16, v193
	s_nop 1
	v_permlane32_swap_b32 v213, v214
	s_nop 0
	v_add_f32_e32 v213, v213, v214
	s_nop 1
	v_add_f32_dpp v213, v213, v213 quad_perm:[1,0,3,2] row_mask:0xf bank_mask:0xf
	s_nop 1
	v_add_f32_dpp v213, v213, v213 quad_perm:[2,3,0,1] row_mask:0xf bank_mask:0xf
	s_nop 1
	v_add_f32_dpp v213, v213, v213 row_half_mirror row_mask:0xf bank_mask:0xf
	s_nop 1
	v_add_f32_dpp v213, v213, v213 row_mirror row_mask:0xf bank_mask:0xf
	s_nop 1
	v_add_f32_dpp v213, v213, v213 row_bcast:15 row_mask:0xa bank_mask:0xf
	s_nop 1
	v_readlane_b32 s28, v213, 31
	v_readlane_b32 s30, v213, 63
	s_nop 1
	v_mov_b32_e32 v215, s28
	v_max_f32_e32 v215, 0x179abe15, v215
	v_rsq_f32_e32 v215, v215
	v_mov_b32_e32 v19, v20
	v_mul_f32_e32 v211, v211, v215
	v_mul_f32_e64 v24, -v211, v8
	v_mul_f32_e32 v216, v211, v31
	v_mul_f32_e32 v8, v8, v30
	v_rcp_f32_e32 v217, v8
	s_nop 0
	v_mul_f32_e32 v16, v216, v217
	v_mul_f32_e32 v17, v212, v217
	ds_write_b32 v1, v16 offset:256
	s_nop 1
	v_permlane32_swap_b32 v16, v17
	ds_write_b32 v1, v24
	ds_read_b128 v[32:35], v2 offset:0
	ds_read_b128 v[36:39], v2 offset:32
	ds_read_b128 v[40:43], v2 offset:64
	ds_read_b128 v[44:47], v2 offset:96
	ds_read_b128 v[48:51], v2 offset:128
	ds_read_b128 v[52:55], v2 offset:160
	ds_read_b128 v[56:59], v2 offset:192
	ds_read_b128 v[60:63], v2 offset:224
	s_waitcnt lgkmcnt(7)
	v_pk_mul_f32 v[220:221], v[64:65], v[32:33]
	v_pk_mul_f32 v[224:225], v[128:129], v[32:33]
	v_pk_mul_f32 v[222:223], v[80:81], v[32:33]
	v_pk_mul_f32 v[226:227], v[144:145], v[32:33]
	v_pk_fma_f32 v[220:221], v[66:67], v[34:35], v[220:221]
	v_pk_fma_f32 v[224:225], v[130:131], v[34:35], v[224:225]
	v_pk_fma_f32 v[222:223], v[82:83], v[34:35], v[222:223]
	v_pk_fma_f32 v[226:227], v[146:147], v[34:35], v[226:227]
	s_waitcnt lgkmcnt(6)
	v_pk_fma_f32 v[220:221], v[68:69], v[36:37], v[220:221]
	v_pk_fma_f32 v[224:225], v[132:133], v[36:37], v[224:225]
	v_pk_fma_f32 v[222:223], v[84:85], v[36:37], v[222:223]
	v_pk_fma_f32 v[226:227], v[148:149], v[36:37], v[226:227]
	v_pk_fma_f32 v[220:221], v[70:71], v[38:39], v[220:221]
	v_pk_fma_f32 v[224:225], v[134:135], v[38:39], v[224:225]
	v_pk_fma_f32 v[222:223], v[86:87], v[38:39], v[222:223]
	v_pk_fma_f32 v[226:227], v[150:151], v[38:39], v[226:227]
	s_waitcnt lgkmcnt(5)
	v_pk_fma_f32 v[220:221], v[72:73], v[40:41], v[220:221]
	v_pk_fma_f32 v[224:225], v[136:137], v[40:41], v[224:225]
	v_pk_fma_f32 v[222:223], v[88:89], v[40:41], v[222:223]
	v_pk_fma_f32 v[226:227], v[152:153], v[40:41], v[226:227]
	v_pk_fma_f32 v[220:221], v[74:75], v[42:43], v[220:221]
	v_pk_fma_f32 v[224:225], v[138:139], v[42:43], v[224:225]
	v_pk_fma_f32 v[222:223], v[90:91], v[42:43], v[222:223]
	v_pk_fma_f32 v[226:227], v[154:155], v[42:43], v[226:227]
	s_waitcnt lgkmcnt(4)
	v_pk_fma_f32 v[220:221], v[76:77], v[44:45], v[220:221]
	v_pk_fma_f32 v[224:225], v[140:141], v[44:45], v[224:225]
	v_pk_fma_f32 v[222:223], v[92:93], v[44:45], v[222:223]
	v_pk_fma_f32 v[226:227], v[156:157], v[44:45], v[226:227]
	v_pk_fma_f32 v[220:221], v[78:79], v[46:47], v[220:221]
	v_pk_fma_f32 v[224:225], v[142:143], v[46:47], v[224:225]
	v_pk_fma_f32 v[222:223], v[94:95], v[46:47], v[222:223]
	v_pk_fma_f32 v[226:227], v[158:159], v[46:47], v[226:227]
	s_waitcnt lgkmcnt(3)
	v_pk_fma_f32 v[220:221], v[96:97], v[48:49], v[220:221]
	v_pk_fma_f32 v[224:225], v[160:161], v[48:49], v[224:225]
	v_pk_fma_f32 v[222:223], v[112:113], v[48:49], v[222:223]
	v_pk_fma_f32 v[226:227], v[176:177], v[48:49], v[226:227]
	v_pk_fma_f32 v[220:221], v[98:99], v[50:51], v[220:221]
	v_pk_fma_f32 v[224:225], v[162:163], v[50:51], v[224:225]
	v_pk_fma_f32 v[222:223], v[114:115], v[50:51], v[222:223]
	v_pk_fma_f32 v[226:227], v[178:179], v[50:51], v[226:227]
	s_waitcnt lgkmcnt(2)
	v_pk_fma_f32 v[220:221], v[100:101], v[52:53], v[220:221]
	v_pk_fma_f32 v[224:225], v[164:165], v[52:53], v[224:225]
	v_pk_fma_f32 v[222:223], v[116:117], v[52:53], v[222:223]
	v_pk_fma_f32 v[226:227], v[180:181], v[52:53], v[226:227]
	v_pk_fma_f32 v[220:221], v[102:103], v[54:55], v[220:221]
	v_pk_fma_f32 v[224:225], v[166:167], v[54:55], v[224:225]
	v_pk_fma_f32 v[222:223], v[118:119], v[54:55], v[222:223]
	v_pk_fma_f32 v[226:227], v[182:183], v[54:55], v[226:227]
	s_waitcnt lgkmcnt(1)
	v_pk_fma_f32 v[220:221], v[104:105], v[56:57], v[220:221]
	v_pk_fma_f32 v[224:225], v[168:169], v[56:57], v[224:225]
	v_pk_fma_f32 v[222:223], v[120:121], v[56:57], v[222:223]
	v_pk_fma_f32 v[226:227], v[184:185], v[56:57], v[226:227]
	v_pk_fma_f32 v[220:221], v[106:107], v[58:59], v[220:221]
	v_pk_fma_f32 v[224:225], v[170:171], v[58:59], v[224:225]
	v_pk_fma_f32 v[222:223], v[122:123], v[58:59], v[222:223]
	v_pk_fma_f32 v[226:227], v[186:187], v[58:59], v[226:227]
	s_waitcnt lgkmcnt(0)
	v_pk_fma_f32 v[220:221], v[108:109], v[60:61], v[220:221]
	v_pk_fma_f32 v[224:225], v[172:173], v[60:61], v[224:225]
	v_pk_fma_f32 v[222:223], v[124:125], v[60:61], v[222:223]
	v_pk_fma_f32 v[226:227], v[188:189], v[60:61], v[226:227]
	v_pk_fma_f32 v[220:221], v[110:111], v[62:63], v[220:221]
	v_pk_fma_f32 v[224:225], v[174:175], v[62:63], v[224:225]
	v_pk_fma_f32 v[222:223], v[126:127], v[62:63], v[222:223]
	v_pk_fma_f32 v[226:227], v[190:191], v[62:63], v[226:227]
	v_add_f32_e32 v18, v220, v221
	v_add_f32_e32 v208, v222, v223
	s_nop 1
	v_permlane32_swap_b32 v18, v208
	s_nop 0
	v_add_f32_e32 v18, v18, v208
	v_add_f32_e32 v228, v224, v225
	v_add_f32_e32 v230, v226, v227
	v_mov_b32_e32 v229, v228
	v_mov_b32_e32 v231, v230
	s_nop 1
	v_permlane32_swap_b32 v228, v229
	v_permlane32_swap_b32 v230, v231
	v_add_f32_e32 v228, v228, v229
	v_add_f32_e32 v230, v230, v231
	s_mov_b32 s18, 0
; DI float rl(float x, int l) { return __int_as_float(__builtin_amdgcn_readlane(__float_as_int(x), l)); }
; template <bool PASS2>
; DI void rwkv_item(const Params& p, int l, int item, int lane, const bf16_t* rkv, const bf16_t* lo2, float* rwst) {
;     ...
;   for (int t = 0; t < LCR; t++) {
;     Raw rawC = rawB;
;     if (t + 2 < LCR) rawC = load_raw(tok0 + t + 2);
;     Der nxt = cur;
;     if (t + 1 < LCR) nxt = derive(rawB, rpA, kpA);
;     const float rr = cur.rr, wdec = cur.wdec, kf = cur.kf, av = cur.av, bv = cur.bv, v = cur.v, gg = cur.gg;
;     float sa0 = 0.f, sa1 = 0.f, pa0 = 0.f, pa1 = 0.f;
; #pragma unroll
;     for (int j = 0; j < 64; j += 2) {
;       const float a0 = rl(av, j), a1 = rl(av, j + 1);
;       sa0 += S[j] * a0; sa1 += S[j + 1] * a1;
;       if (!PASS2) { pa0 += P[j] * a0; pa1 += P[j + 1] * a1; }
;     }
;     const float sa = sa0 + sa1, pa = pa0 + pa1;
;     float y0 = 0.f, y1 = 0.f;
; #pragma unroll
;     for (int j = 0; j < 64; j += 2) {
;       const float w0 = rl(wdec, j), b0 = rl(bv, j), k0 = rl(kf, j);
;       const float w1 = rl(wdec, j + 1), b1 = rl(bv, j + 1), k1 = rl(kf, j + 1);
;       S[j] = S[j] * w0 + sa * b0 + v * k0;
;       S[j + 1] = S[j + 1] * w1 + sa * b1 + v * k1;
;       if (!PASS2) {
;         P[j] = P[j] * w0 + pa * b0;
;         P[j + 1] = P[j + 1] * w1 + pa * b1;
;       } else {
;         y0 += S[j] * rl(rr, j); y1 += S[j + 1] * rl(rr, j + 1);
;       }
;     }
.Lrwp1a_loop:
	s_nop 1
	v_permlane32_swap_b32 v18, v19
	s_nop 1
	v_mfma_f32_32x32x2_f32 v[64:79], v16, v18, v[64:79]
	ds_read_b128 v[32:35], v2 offset:256
	ds_read_b128 v[36:39], v2 offset:288
	ds_read_b128 v[40:43], v2 offset:320
	ds_read_b128 v[44:47], v2 offset:352
	ds_read_b128 v[48:51], v2 offset:384
	ds_read_b128 v[52:55], v2 offset:416
	ds_read_b128 v[56:59], v2 offset:448
	ds_read_b128 v[60:63], v2 offset:480
	s_waitcnt lgkmcnt(7)
	v_pk_fma_f32 v[128:129], v[32:33], v[228:229], v[128:129] op_sel_hi:[1,0,1]
	v_pk_fma_f32 v[144:145], v[32:33], v[230:231], v[144:145] op_sel_hi:[1,0,1]
	v_pk_fma_f32 v[130:131], v[34:35], v[228:229], v[130:131] op_sel_hi:[1,0,1]
	v_pk_fma_f32 v[146:147], v[34:35], v[230:231], v[146:147] op_sel_hi:[1,0,1]
	s_waitcnt lgkmcnt(6)
	v_pk_fma_f32 v[132:133], v[36:37], v[228:229], v[132:133] op_sel_hi:[1,0,1]
	v_pk_fma_f32 v[148:149], v[36:37], v[230:231], v[148:149] op_sel_hi:[1,0,1]
	v_pk_fma_f32 v[134:135], v[38:39], v[228:229], v[134:135] op_sel_hi:[1,0,1]
	v_pk_fma_f32 v[150:151], v[38:39], v[230:231], v[150:151] op_sel_hi:[1,0,1]
	s_waitcnt lgkmcnt(5)
	v_pk_fma_f32 v[136:137], v[40:41], v[228:229], v[136:137] op_sel_hi:[1,0,1]
	v_pk_fma_f32 v[152:153], v[40:41], v[230:231], v[152:153] op_sel_hi:[1,0,1]
	v_pk_fma_f32 v[138:139], v[42:43], v[228:229], v[138:139] op_sel_hi:[1,0,1]
	v_pk_fma_f32 v[154:155], v[42:43], v[230:231], v[154:155] op_sel_hi:[1,0,1]
	s_waitcnt lgkmcnt(4)
	v_pk_fma_f32 v[140:141], v[44:45], v[228:229], v[140:141] op_sel_hi:[1,0,1]
	v_pk_fma_f32 v[156:157], v[44:45], v[230:231], v[156:157] op_sel_hi:[1,0,1]
	v_pk_fma_f32 v[142:143], v[46:47], v[228:229], v[142:143] op_sel_hi:[1,0,1]
	v_pk_fma_f32 v[158:159], v[46:47], v[230:231], v[158:159] op_sel_hi:[1,0,1]
	s_waitcnt lgkmcnt(3)
	v_pk_fma_f32 v[160:161], v[48:49], v[228:229], v[160:161] op_sel_hi:[1,0,1]
	v_pk_fma_f32 v[176:177], v[48:49], v[230:231], v[176:177] op_sel_hi:[1,0,1]
	v_pk_fma_f32 v[162:163], v[50:51], v[228:229], v[162:163] op_sel_hi:[1,0,1]
	v_pk_fma_f32 v[178:179], v[50:51], v[230:231], v[178:179] op_sel_hi:[1,0,1]
	s_waitcnt lgkmcnt(2)
	v_pk_fma_f32 v[164:165], v[52:53], v[228:229], v[164:165] op_sel_hi:[1,0,1]
	v_pk_fma_f32 v[180:181], v[52:53], v[230:231], v[180:181] op_sel_hi:[1,0,1]
	v_pk_fma_f32 v[166:167], v[54:55], v[228:229], v[166:167] op_sel_hi:[1,0,1]
	v_pk_fma_f32 v[182:183], v[54:55], v[230:231], v[182:183] op_sel_hi:[1,0,1]
	s_waitcnt lgkmcnt(1)
	v_pk_fma_f32 v[168:169], v[56:57], v[228:229], v[168:169] op_sel_hi:[1,0,1]
	v_pk_fma_f32 v[184:185], v[56:57], v[230:231], v[184:185] op_sel_hi:[1,0,1]
	v_pk_fma_f32 v[170:171], v[58:59], v[228:229], v[170:171] op_sel_hi:[1,0,1]
	v_pk_fma_f32 v[186:187], v[58:59], v[230:231], v[186:187] op_sel_hi:[1,0,1]
	s_waitcnt lgkmcnt(0)
	v_pk_fma_f32 v[172:173], v[60:61], v[228:229], v[172:173] op_sel_hi:[1,0,1]
	v_pk_fma_f32 v[188:189], v[60:61], v[230:231], v[188:189] op_sel_hi:[1,0,1]
	v_pk_fma_f32 v[174:175], v[62:63], v[228:229], v[174:175] op_sel_hi:[1,0,1]
	v_pk_fma_f32 v[190:191], v[62:63], v[230:231], v[190:191] op_sel_hi:[1,0,1]
	global_load_ushort v192, v3, s[4:5] offset:1024
	global_load_ushort v193, v4, s[6:7]
	global_load_ushort v194, v4, s[8:9]
	global_load_ushort v195, v4, s[10:11]
	v_add_u32_e32 v3, 0xc00, v3
	v_add_u32_e32 v4, 0x400, v4
	s_waitcnt vmcnt(12)
	v_lshlrev_b32_e32 v27, 16, v196
	v_sub_f32_e32 v29, v7, v27
	v_fma_f32 v29, v29, v10, v27
	v_mov_b32_e32 v7, v27
	v_lshlrev_b32_e32 v30, 16, v198
	v_mul_f32_e32 v30, 0xbfb8aa3b, v30
	v_exp_f32_e32 v30, v30
	v_lshlrev_b32_e32 v31, 16, v199
	v_mfma_f32_32x32x2_f32 v[80:95], v16, v19, v[80:95]
	v_mul_f32_e32 v211, v29, v11
	v_add_f32_e32 v212, -1.0, v31
	v_fma_f32 v212, v212, v12, 1.0
	v_mul_f32_e32 v212, v29, v212
	v_mul_f32_e32 v213, v211, v211
	v_mov_b32_e32 v214, 0
	v_lshlrev_b32_e32 v21, 16, v197
	s_nop 1
	v_mfma_f32_32x32x2_f32 v[96:111], v17, v18, v[96:111]
	v_permlane32_swap_b32 v213, v214
	s_nop 0
	v_add_f32_e32 v213, v213, v214
	s_nop 1
	v_add_f32_dpp v213, v213, v213 quad_perm:[1,0,3,2] row_mask:0xf bank_mask:0xf
	s_nop 1
	v_add_f32_dpp v213, v213, v213 quad_perm:[2,3,0,1] row_mask:0xf bank_mask:0xf
	s_nop 1
	v_mfma_f32_32x32x2_f32 v[112:127], v17, v19, v[112:127]
	v_add_f32_dpp v213, v213, v213 row_half_mirror row_mask:0xf bank_mask:0xf
	s_nop 1
	v_add_f32_dpp v213, v213, v213 row_mirror row_mask:0xf bank_mask:0xf
	s_nop 1
	v_add_f32_dpp v213, v213, v213 row_bcast:15 row_mask:0xa bank_mask:0xf
	s_nop 1
	v_readlane_b32 s28, v213, 31
	v_readlane_b32 s31, v213, 63
	s_nop 1
	v_mov_b32_e32 v215, s28
	v_max_f32_e32 v215, 0x179abe15, v215
	v_rsq_f32_e32 v215, v215
	v_mov_b32_e32 v19, v21
	v_mul_f32_e32 v211, v211, v215
	v_mul_f32_e64 v24, -v211, v8
	v_mul_f32_e32 v216, v211, v31
	v_mul_f32_e32 v8, v8, v30
	v_rcp_f32_e32 v217, v8
	s_nop 0
	v_mul_f32_e32 v16, v216, v217
	v_mul_f32_e32 v17, v212, v217
	ds_write_b32 v1, v16 offset:256
	s_nop 1
	v_permlane32_swap_b32 v16, v17
	ds_write_b32 v1, v24
	ds_read_b128 v[32:35], v2 offset:0
	ds_read_b128 v[36:39], v2 offset:32
	ds_read_b128 v[40:43], v2 offset:64
	ds_read_b128 v[44:47], v2 offset:96
	ds_read_b128 v[48:51], v2 offset:128
	ds_read_b128 v[52:55], v2 offset:160
	ds_read_b128 v[56:59], v2 offset:192
	ds_read_b128 v[60:63], v2 offset:224
	s_waitcnt lgkmcnt(7)
	v_pk_mul_f32 v[220:221], v[64:65], v[32:33]
	v_pk_mul_f32 v[224:225], v[128:129], v[32:33]
	v_pk_mul_f32 v[222:223], v[80:81], v[32:33]
	v_pk_mul_f32 v[226:227], v[144:145], v[32:33]
	v_pk_fma_f32 v[220:221], v[66:67], v[34:35], v[220:221]
	v_pk_fma_f32 v[224:225], v[130:131], v[34:35], v[224:225]
	v_pk_fma_f32 v[222:223], v[82:83], v[34:35], v[222:223]
	v_pk_fma_f32 v[226:227], v[146:147], v[34:35], v[226:227]
	s_waitcnt lgkmcnt(6)
; DI float rl(float x, int l) { return __int_as_float(__builtin_amdgcn_readlane(__float_as_int(x), l)); }
; template <bool PASS2>
; DI void rwkv_item(const Params& p, int l, int item, int lane, const bf16_t* rkv, const bf16_t* lo2, float* rwst) {
;     ...
;     float sa0 = 0.f, sa1 = 0.f, pa0 = 0.f, pa1 = 0.f;
; #pragma unroll
;     for (int j = 0; j < 64; j += 2) {
;       const float a0 = rl(av, j), a1 = rl(av, j + 1);
;       sa0 += S[j] * a0; sa1 += S[j + 1] * a1;
;       if (!PASS2) { pa0 += P[j] * a0; pa1 += P[j + 1] * a1; }
;     }
;     const float sa = sa0 + sa1, pa = pa0 + pa1;
;     float y0 = 0.f, y1 = 0.f;
; #pragma unroll
;     for (int j = 0; j < 64; j += 2) {
;       const float w0 = rl(wdec, j), b0 = rl(bv, j), k0 = rl(kf, j);
;       const float w1 = rl(wdec, j + 1), b1 = rl(bv, j + 1), k1 = rl(kf, j + 1);
;       S[j] = S[j] * w0 + sa * b0 + v * k0;
;       S[j + 1] = S[j + 1] * w1 + sa * b1 + v * k1;
;       if (!PASS2) {
;         P[j] = P[j] * w0 + pa * b0;
;         P[j + 1] = P[j + 1] * w1 + pa * b1;
;       } else {
;         y0 += S[j] * rl(rr, j); y1 += S[j + 1] * rl(rr, j + 1);
;       }
;     }
	v_pk_fma_f32 v[220:221], v[68:69], v[36:37], v[220:221]
	v_pk_fma_f32 v[224:225], v[132:133], v[36:37], v[224:225]
	v_pk_fma_f32 v[222:223], v[84:85], v[36:37], v[222:223]
	v_pk_fma_f32 v[226:227], v[148:149], v[36:37], v[226:227]
	v_pk_fma_f32 v[220:221], v[70:71], v[38:39], v[220:221]
	v_pk_fma_f32 v[224:225], v[134:135], v[38:39], v[224:225]
	v_pk_fma_f32 v[222:223], v[86:87], v[38:39], v[222:223]
	v_pk_fma_f32 v[226:227], v[150:151], v[38:39], v[226:227]
	s_waitcnt lgkmcnt(5)
	v_pk_fma_f32 v[220:221], v[72:73], v[40:41], v[220:221]
	v_pk_fma_f32 v[224:225], v[136:137], v[40:41], v[224:225]
	v_pk_fma_f32 v[222:223], v[88:89], v[40:41], v[222:223]
	v_pk_fma_f32 v[226:227], v[152:153], v[40:41], v[226:227]
	v_pk_fma_f32 v[220:221], v[74:75], v[42:43], v[220:221]
	v_pk_fma_f32 v[224:225], v[138:139], v[42:43], v[224:225]
	v_pk_fma_f32 v[222:223], v[90:91], v[42:43], v[222:223]
	v_pk_fma_f32 v[226:227], v[154:155], v[42:43], v[226:227]
	s_waitcnt lgkmcnt(4)
	v_pk_fma_f32 v[220:221], v[76:77], v[44:45], v[220:221]
	v_pk_fma_f32 v[224:225], v[140:141], v[44:45], v[224:225]
	v_pk_fma_f32 v[222:223], v[92:93], v[44:45], v[222:223]
	v_pk_fma_f32 v[226:227], v[156:157], v[44:45], v[226:227]
	v_pk_fma_f32 v[220:221], v[78:79], v[46:47], v[220:221]
	v_pk_fma_f32 v[224:225], v[142:143], v[46:47], v[224:225]
	v_pk_fma_f32 v[222:223], v[94:95], v[46:47], v[222:223]
	v_pk_fma_f32 v[226:227], v[158:159], v[46:47], v[226:227]
	s_waitcnt lgkmcnt(3)
	v_pk_fma_f32 v[220:221], v[96:97], v[48:49], v[220:221]
	v_pk_fma_f32 v[224:225], v[160:161], v[48:49], v[224:225]
	v_pk_fma_f32 v[222:223], v[112:113], v[48:49], v[222:223]
	v_pk_fma_f32 v[226:227], v[176:177], v[48:49], v[226:227]
	v_pk_fma_f32 v[220:221], v[98:99], v[50:51], v[220:221]
	v_pk_fma_f32 v[224:225], v[162:163], v[50:51], v[224:225]
	v_pk_fma_f32 v[222:223], v[114:115], v[50:51], v[222:223]
	v_pk_fma_f32 v[226:227], v[178:179], v[50:51], v[226:227]
	s_waitcnt lgkmcnt(2)
	v_pk_fma_f32 v[220:221], v[100:101], v[52:53], v[220:221]
	v_pk_fma_f32 v[224:225], v[164:165], v[52:53], v[224:225]
	v_pk_fma_f32 v[222:223], v[116:117], v[52:53], v[222:223]
	v_pk_fma_f32 v[226:227], v[180:181], v[52:53], v[226:227]
	v_pk_fma_f32 v[220:221], v[102:103], v[54:55], v[220:221]
	v_pk_fma_f32 v[224:225], v[166:167], v[54:55], v[224:225]
	v_pk_fma_f32 v[222:223], v[118:119], v[54:55], v[222:223]
	v_pk_fma_f32 v[226:227], v[182:183], v[54:55], v[226:227]
	s_waitcnt lgkmcnt(1)
	v_pk_fma_f32 v[220:221], v[104:105], v[56:57], v[220:221]
	v_pk_fma_f32 v[224:225], v[168:169], v[56:57], v[224:225]
	v_pk_fma_f32 v[222:223], v[120:121], v[56:57], v[222:223]
	v_pk_fma_f32 v[226:227], v[184:185], v[56:57], v[226:227]
	v_pk_fma_f32 v[220:221], v[106:107], v[58:59], v[220:221]
	v_pk_fma_f32 v[224:225], v[170:171], v[58:59], v[224:225]
	v_pk_fma_f32 v[222:223], v[122:123], v[58:59], v[222:223]
	v_pk_fma_f32 v[226:227], v[186:187], v[58:59], v[226:227]
	s_waitcnt lgkmcnt(0)
	v_pk_fma_f32 v[220:221], v[108:109], v[60:61], v[220:221]
	v_pk_fma_f32 v[224:225], v[172:173], v[60:61], v[224:225]
	v_pk_fma_f32 v[222:223], v[124:125], v[60:61], v[222:223]
	v_pk_fma_f32 v[226:227], v[188:189], v[60:61], v[226:227]
	v_pk_fma_f32 v[220:221], v[110:111], v[62:63], v[220:221]
	v_pk_fma_f32 v[224:225], v[174:175], v[62:63], v[224:225]
	v_pk_fma_f32 v[222:223], v[126:127], v[62:63], v[222:223]
	v_pk_fma_f32 v[226:227], v[190:191], v[62:63], v[226:227]
	v_add_f32_e32 v18, v220, v221
	v_add_f32_e32 v208, v222, v223
	s_nop 1
	v_permlane32_swap_b32 v18, v208
	s_nop 0
	v_add_f32_e32 v18, v18, v208
	v_add_f32_e32 v228, v224, v225
	v_add_f32_e32 v230, v226, v227
	v_mov_b32_e32 v229, v228
	v_mov_b32_e32 v231, v230
	s_nop 1
	v_permlane32_swap_b32 v228, v229
	v_permlane32_swap_b32 v230, v231
	v_add_f32_e32 v228, v228, v229
	v_add_f32_e32 v230, v230, v231
	s_nop 1
	v_permlane32_swap_b32 v18, v19
	s_nop 1
	v_mfma_f32_32x32x2_f32 v[64:79], v16, v18, v[64:79]
	ds_read_b128 v[32:35], v2 offset:256
	ds_read_b128 v[36:39], v2 offset:288
	ds_read_b128 v[40:43], v2 offset:320
	ds_read_b128 v[44:47], v2 offset:352
	ds_read_b128 v[48:51], v2 offset:384
	ds_read_b128 v[52:55], v2 offset:416
	ds_read_b128 v[56:59], v2 offset:448
	ds_read_b128 v[60:63], v2 offset:480
	s_waitcnt lgkmcnt(7)
	v_pk_fma_f32 v[128:129], v[32:33], v[228:229], v[128:129] op_sel_hi:[1,0,1]
	v_pk_fma_f32 v[144:145], v[32:33], v[230:231], v[144:145] op_sel_hi:[1,0,1]
	v_pk_fma_f32 v[130:131], v[34:35], v[228:229], v[130:131] op_sel_hi:[1,0,1]
	v_pk_fma_f32 v[146:147], v[34:35], v[230:231], v[146:147] op_sel_hi:[1,0,1]
	s_waitcnt lgkmcnt(6)
	v_pk_fma_f32 v[132:133], v[36:37], v[228:229], v[132:133] op_sel_hi:[1,0,1]
	v_pk_fma_f32 v[148:149], v[36:37], v[230:231], v[148:149] op_sel_hi:[1,0,1]
	v_pk_fma_f32 v[134:135], v[38:39], v[228:229], v[134:135] op_sel_hi:[1,0,1]
	v_pk_fma_f32 v[150:151], v[38:39], v[230:231], v[150:151] op_sel_hi:[1,0,1]
	s_waitcnt lgkmcnt(5)
	v_pk_fma_f32 v[136:137], v[40:41], v[228:229], v[136:137] op_sel_hi:[1,0,1]
	v_pk_fma_f32 v[152:153], v[40:41], v[230:231], v[152:153] op_sel_hi:[1,0,1]
	v_pk_fma_f32 v[138:139], v[42:43], v[228:229], v[138:139] op_sel_hi:[1,0,1]
	v_pk_fma_f32 v[154:155], v[42:43], v[230:231], v[154:155] op_sel_hi:[1,0,1]
	s_waitcnt lgkmcnt(4)
	v_pk_fma_f32 v[140:141], v[44:45], v[228:229], v[140:141] op_sel_hi:[1,0,1]
	v_pk_fma_f32 v[156:157], v[44:45], v[230:231], v[156:157] op_sel_hi:[1,0,1]
	v_pk_fma_f32 v[142:143], v[46:47], v[228:229], v[142:143] op_sel_hi:[1,0,1]
	v_pk_fma_f32 v[158:159], v[46:47], v[230:231], v[158:159] op_sel_hi:[1,0,1]
	s_waitcnt lgkmcnt(3)
; DI float rl(float x, int l) { return __int_as_float(__builtin_amdgcn_readlane(__float_as_int(x), l)); }
; template <bool PASS2>
; DI void rwkv_item(const Params& p, int l, int item, int lane, const bf16_t* rkv, const bf16_t* lo2, float* rwst) {
;     ...
;   for (int t = 0; t < LCR; t++) {
;     Raw rawC = rawB;
;     if (t + 2 < LCR) rawC = load_raw(tok0 + t + 2);
;     Der nxt = cur;
;     if (t + 1 < LCR) nxt = derive(rawB, rpA, kpA);
;     const float rr = cur.rr, wdec = cur.wdec, kf = cur.kf, av = cur.av, bv = cur.bv, v = cur.v, gg = cur.gg;
;     float sa0 = 0.f, sa1 = 0.f, pa0 = 0.f, pa1 = 0.f;
; #pragma unroll
;     for (int j = 0; j < 64; j += 2) {
;       const float a0 = rl(av, j), a1 = rl(av, j + 1);
;       sa0 += S[j] * a0; sa1 += S[j + 1] * a1;
;       if (!PASS2) { pa0 += P[j] * a0; pa1 += P[j + 1] * a1; }
;     }
;     const float sa = sa0 + sa1, pa = pa0 + pa1;
;     float y0 = 0.f, y1 = 0.f;
; #pragma unroll
;     for (int j = 0; j < 64; j += 2) {
;       const float w0 = rl(wdec, j), b0 = rl(bv, j), k0 = rl(kf, j);
;       const float w1 = rl(wdec, j + 1), b1 = rl(bv, j + 1), k1 = rl(kf, j + 1);
;       S[j] = S[j] * w0 + sa * b0 + v * k0;
;       S[j + 1] = S[j + 1] * w1 + sa * b1 + v * k1;
;       if (!PASS2) {
;         P[j] = P[j] * w0 + pa * b0;
;         P[j + 1] = P[j + 1] * w1 + pa * b1;
;       } else {
;         y0 += S[j] * rl(rr, j); y1 += S[j + 1] * rl(rr, j + 1);
;       }
;     }
	v_pk_fma_f32 v[160:161], v[48:49], v[228:229], v[160:161] op_sel_hi:[1,0,1]
	v_pk_fma_f32 v[176:177], v[48:49], v[230:231], v[176:177] op_sel_hi:[1,0,1]
	v_pk_fma_f32 v[162:163], v[50:51], v[228:229], v[162:163] op_sel_hi:[1,0,1]
	v_pk_fma_f32 v[178:179], v[50:51], v[230:231], v[178:179] op_sel_hi:[1,0,1]
	s_waitcnt lgkmcnt(2)
	v_pk_fma_f32 v[164:165], v[52:53], v[228:229], v[164:165] op_sel_hi:[1,0,1]
	v_pk_fma_f32 v[180:181], v[52:53], v[230:231], v[180:181] op_sel_hi:[1,0,1]
	v_pk_fma_f32 v[166:167], v[54:55], v[228:229], v[166:167] op_sel_hi:[1,0,1]
	v_pk_fma_f32 v[182:183], v[54:55], v[230:231], v[182:183] op_sel_hi:[1,0,1]
	s_waitcnt lgkmcnt(1)
	v_pk_fma_f32 v[168:169], v[56:57], v[228:229], v[168:169] op_sel_hi:[1,0,1]
	v_pk_fma_f32 v[184:185], v[56:57], v[230:231], v[184:185] op_sel_hi:[1,0,1]
	v_pk_fma_f32 v[170:171], v[58:59], v[228:229], v[170:171] op_sel_hi:[1,0,1]
	v_pk_fma_f32 v[186:187], v[58:59], v[230:231], v[186:187] op_sel_hi:[1,0,1]
	s_waitcnt lgkmcnt(0)
	v_pk_fma_f32 v[172:173], v[60:61], v[228:229], v[172:173] op_sel_hi:[1,0,1]
	v_pk_fma_f32 v[188:189], v[60:61], v[230:231], v[188:189] op_sel_hi:[1,0,1]
	v_pk_fma_f32 v[174:175], v[62:63], v[228:229], v[174:175] op_sel_hi:[1,0,1]
	v_pk_fma_f32 v[190:191], v[62:63], v[230:231], v[190:191] op_sel_hi:[1,0,1]
	global_load_ushort v196, v3, s[4:5] offset:1024
	global_load_ushort v197, v4, s[6:7]
	global_load_ushort v198, v4, s[8:9]
	global_load_ushort v199, v4, s[10:11]
	v_add_u32_e32 v3, 0xc00, v3
	v_add_u32_e32 v4, 0x400, v4
	s_waitcnt vmcnt(12)
	v_lshlrev_b32_e32 v27, 16, v200
	v_sub_f32_e32 v29, v7, v27
	v_fma_f32 v29, v29, v10, v27
	v_mov_b32_e32 v7, v27
	v_lshlrev_b32_e32 v30, 16, v202
	v_mul_f32_e32 v30, 0xbfb8aa3b, v30
	v_exp_f32_e32 v30, v30
	v_lshlrev_b32_e32 v31, 16, v203
	v_mfma_f32_32x32x2_f32 v[80:95], v16, v19, v[80:95]
	v_mul_f32_e32 v211, v29, v11
	v_add_f32_e32 v212, -1.0, v31
	v_fma_f32 v212, v212, v12, 1.0
	v_mul_f32_e32 v212, v29, v212
	v_mul_f32_e32 v213, v211, v211
	v_mov_b32_e32 v214, 0
	v_lshlrev_b32_e32 v20, 16, v201
	s_nop 1
	v_mfma_f32_32x32x2_f32 v[96:111], v17, v18, v[96:111]
	v_permlane32_swap_b32 v213, v214
	s_nop 0
	v_add_f32_e32 v213, v213, v214
	s_nop 1
	v_add_f32_dpp v213, v213, v213 quad_perm:[1,0,3,2] row_mask:0xf bank_mask:0xf
	s_nop 1
	v_add_f32_dpp v213, v213, v213 quad_perm:[2,3,0,1] row_mask:0xf bank_mask:0xf
	s_nop 1
	v_mfma_f32_32x32x2_f32 v[112:127], v17, v19, v[112:127]
	v_add_f32_dpp v213, v213, v213 row_half_mirror row_mask:0xf bank_mask:0xf
	s_nop 1
	v_add_f32_dpp v213, v213, v213 row_mirror row_mask:0xf bank_mask:0xf
	s_nop 1
	v_add_f32_dpp v213, v213, v213 row_bcast:15 row_mask:0xa bank_mask:0xf
	s_nop 1
	v_readlane_b32 s28, v213, 31
	v_readlane_b32 s30, v213, 63
	s_nop 1
	v_mov_b32_e32 v215, s28
	v_max_f32_e32 v215, 0x179abe15, v215
	v_rsq_f32_e32 v215, v215
	v_mov_b32_e32 v19, v20
	v_mul_f32_e32 v211, v211, v215
	v_mul_f32_e64 v24, -v211, v8
	v_mul_f32_e32 v216, v211, v31
	v_mul_f32_e32 v8, v8, v30
	v_rcp_f32_e32 v217, v8
	s_nop 0
	v_mul_f32_e32 v16, v216, v217
	v_mul_f32_e32 v17, v212, v217
	ds_write_b32 v1, v16 offset:256
	s_nop 1
	v_permlane32_swap_b32 v16, v17
	ds_write_b32 v1, v24
	ds_read_b128 v[32:35], v2 offset:0
	ds_read_b128 v[36:39], v2 offset:32
	ds_read_b128 v[40:43], v2 offset:64
	ds_read_b128 v[44:47], v2 offset:96
	ds_read_b128 v[48:51], v2 offset:128
	ds_read_b128 v[52:55], v2 offset:160
	ds_read_b128 v[56:59], v2 offset:192
	ds_read_b128 v[60:63], v2 offset:224
	s_waitcnt lgkmcnt(7)
	v_pk_mul_f32 v[220:221], v[64:65], v[32:33]
	v_pk_mul_f32 v[224:225], v[128:129], v[32:33]
	v_pk_mul_f32 v[222:223], v[80:81], v[32:33]
	v_pk_mul_f32 v[226:227], v[144:145], v[32:33]
	v_pk_fma_f32 v[220:221], v[66:67], v[34:35], v[220:221]
	v_pk_fma_f32 v[224:225], v[130:131], v[34:35], v[224:225]
	v_pk_fma_f32 v[222:223], v[82:83], v[34:35], v[222:223]
	v_pk_fma_f32 v[226:227], v[146:147], v[34:35], v[226:227]
	s_waitcnt lgkmcnt(6)
	v_pk_fma_f32 v[220:221], v[68:69], v[36:37], v[220:221]
	v_pk_fma_f32 v[224:225], v[132:133], v[36:37], v[224:225]
	v_pk_fma_f32 v[222:223], v[84:85], v[36:37], v[222:223]
	v_pk_fma_f32 v[226:227], v[148:149], v[36:37], v[226:227]
	v_pk_fma_f32 v[220:221], v[70:71], v[38:39], v[220:221]
	v_pk_fma_f32 v[224:225], v[134:135], v[38:39], v[224:225]
	v_pk_fma_f32 v[222:223], v[86:87], v[38:39], v[222:223]
	v_pk_fma_f32 v[226:227], v[150:151], v[38:39], v[226:227]
	s_waitcnt lgkmcnt(5)
	v_pk_fma_f32 v[220:221], v[72:73], v[40:41], v[220:221]
	v_pk_fma_f32 v[224:225], v[136:137], v[40:41], v[224:225]
	v_pk_fma_f32 v[222:223], v[88:89], v[40:41], v[222:223]
	v_pk_fma_f32 v[226:227], v[152:153], v[40:41], v[226:227]
	v_pk_fma_f32 v[220:221], v[74:75], v[42:43], v[220:221]
	v_pk_fma_f32 v[224:225], v[138:139], v[42:43], v[224:225]
	v_pk_fma_f32 v[222:223], v[90:91], v[42:43], v[222:223]
	v_pk_fma_f32 v[226:227], v[154:155], v[42:43], v[226:227]
	s_waitcnt lgkmcnt(4)
	v_pk_fma_f32 v[220:221], v[76:77], v[44:45], v[220:221]
	v_pk_fma_f32 v[224:225], v[140:141], v[44:45], v[224:225]
	v_pk_fma_f32 v[222:223], v[92:93], v[44:45], v[222:223]
	v_pk_fma_f32 v[226:227], v[156:157], v[44:45], v[226:227]
	v_pk_fma_f32 v[220:221], v[78:79], v[46:47], v[220:221]
	v_pk_fma_f32 v[224:225], v[142:143], v[46:47], v[224:225]
	v_pk_fma_f32 v[222:223], v[94:95], v[46:47], v[222:223]
	v_pk_fma_f32 v[226:227], v[158:159], v[46:47], v[226:227]
	s_waitcnt lgkmcnt(3)
	v_pk_fma_f32 v[220:221], v[96:97], v[48:49], v[220:221]
	v_pk_fma_f32 v[224:225], v[160:161], v[48:49], v[224:225]
	v_pk_fma_f32 v[222:223], v[112:113], v[48:49], v[222:223]
	v_pk_fma_f32 v[226:227], v[176:177], v[48:49], v[226:227]
	v_pk_fma_f32 v[220:221], v[98:99], v[50:51], v[220:221]
	v_pk_fma_f32 v[224:225], v[162:163], v[50:51], v[224:225]
	v_pk_fma_f32 v[222:223], v[114:115], v[50:51], v[222:223]
	v_pk_fma_f32 v[226:227], v[178:179], v[50:51], v[226:227]
	s_waitcnt lgkmcnt(2)
; DI float rl(float x, int l) { return __int_as_float(__builtin_amdgcn_readlane(__float_as_int(x), l)); }
; template <bool PASS2>
; DI void rwkv_item(const Params& p, int l, int item, int lane, const bf16_t* rkv, const bf16_t* lo2, float* rwst) {
;     ...
;     float sa0 = 0.f, sa1 = 0.f, pa0 = 0.f, pa1 = 0.f;
; #pragma unroll
;     for (int j = 0; j < 64; j += 2) {
;       const float a0 = rl(av, j), a1 = rl(av, j + 1);
;       sa0 += S[j] * a0; sa1 += S[j + 1] * a1;
;       if (!PASS2) { pa0 += P[j] * a0; pa1 += P[j + 1] * a1; }
;     }
;     const float sa = sa0 + sa1, pa = pa0 + pa1;
;     float y0 = 0.f, y1 = 0.f;
; #pragma unroll
;     for (int j = 0; j < 64; j += 2) {
;       const float w0 = rl(wdec, j), b0 = rl(bv, j), k0 = rl(kf, j);
;       const float w1 = rl(wdec, j + 1), b1 = rl(bv, j + 1), k1 = rl(kf, j + 1);
;       S[j] = S[j] * w0 + sa * b0 + v * k0;
;       S[j + 1] = S[j + 1] * w1 + sa * b1 + v * k1;
;       if (!PASS2) {
;         P[j] = P[j] * w0 + pa * b0;
;         P[j + 1] = P[j + 1] * w1 + pa * b1;
;       } else {
;         y0 += S[j] * rl(rr, j); y1 += S[j + 1] * rl(rr, j + 1);
;       }
;     }
	v_pk_fma_f32 v[220:221], v[100:101], v[52:53], v[220:221]
	v_pk_fma_f32 v[224:225], v[164:165], v[52:53], v[224:225]
	v_pk_fma_f32 v[222:223], v[116:117], v[52:53], v[222:223]
	v_pk_fma_f32 v[226:227], v[180:181], v[52:53], v[226:227]
	v_pk_fma_f32 v[220:221], v[102:103], v[54:55], v[220:221]
	v_pk_fma_f32 v[224:225], v[166:167], v[54:55], v[224:225]
	v_pk_fma_f32 v[222:223], v[118:119], v[54:55], v[222:223]
	v_pk_fma_f32 v[226:227], v[182:183], v[54:55], v[226:227]
	s_waitcnt lgkmcnt(1)
	v_pk_fma_f32 v[220:221], v[104:105], v[56:57], v[220:221]
	v_pk_fma_f32 v[224:225], v[168:169], v[56:57], v[224:225]
	v_pk_fma_f32 v[222:223], v[120:121], v[56:57], v[222:223]
	v_pk_fma_f32 v[226:227], v[184:185], v[56:57], v[226:227]
	v_pk_fma_f32 v[220:221], v[106:107], v[58:59], v[220:221]
	v_pk_fma_f32 v[224:225], v[170:171], v[58:59], v[224:225]
	v_pk_fma_f32 v[222:223], v[122:123], v[58:59], v[222:223]
	v_pk_fma_f32 v[226:227], v[186:187], v[58:59], v[226:227]
	s_waitcnt lgkmcnt(0)
	v_pk_fma_f32 v[220:221], v[108:109], v[60:61], v[220:221]
	v_pk_fma_f32 v[224:225], v[172:173], v[60:61], v[224:225]
	v_pk_fma_f32 v[222:223], v[124:125], v[60:61], v[222:223]
	v_pk_fma_f32 v[226:227], v[188:189], v[60:61], v[226:227]
	v_pk_fma_f32 v[220:221], v[110:111], v[62:63], v[220:221]
	v_pk_fma_f32 v[224:225], v[174:175], v[62:63], v[224:225]
	v_pk_fma_f32 v[222:223], v[126:127], v[62:63], v[222:223]
	v_pk_fma_f32 v[226:227], v[190:191], v[62:63], v[226:227]
	v_add_f32_e32 v18, v220, v221
	v_add_f32_e32 v208, v222, v223
	s_nop 1
	v_permlane32_swap_b32 v18, v208
	s_nop 0
	v_add_f32_e32 v18, v18, v208
	v_add_f32_e32 v228, v224, v225
	v_add_f32_e32 v230, v226, v227
	v_mov_b32_e32 v229, v228
	v_mov_b32_e32 v231, v230
	s_nop 1
	v_permlane32_swap_b32 v228, v229
	v_permlane32_swap_b32 v230, v231
	v_add_f32_e32 v228, v228, v229
	v_add_f32_e32 v230, v230, v231
	s_nop 1
	v_permlane32_swap_b32 v18, v19
	s_nop 1
	v_mfma_f32_32x32x2_f32 v[64:79], v16, v18, v[64:79]
	ds_read_b128 v[32:35], v2 offset:256
	ds_read_b128 v[36:39], v2 offset:288
	ds_read_b128 v[40:43], v2 offset:320
	ds_read_b128 v[44:47], v2 offset:352
	ds_read_b128 v[48:51], v2 offset:384
	ds_read_b128 v[52:55], v2 offset:416
	ds_read_b128 v[56:59], v2 offset:448
	ds_read_b128 v[60:63], v2 offset:480
	s_waitcnt lgkmcnt(7)
	v_pk_fma_f32 v[128:129], v[32:33], v[228:229], v[128:129] op_sel_hi:[1,0,1]
	v_pk_fma_f32 v[144:145], v[32:33], v[230:231], v[144:145] op_sel_hi:[1,0,1]
	v_pk_fma_f32 v[130:131], v[34:35], v[228:229], v[130:131] op_sel_hi:[1,0,1]
	v_pk_fma_f32 v[146:147], v[34:35], v[230:231], v[146:147] op_sel_hi:[1,0,1]
	s_waitcnt lgkmcnt(6)
	v_pk_fma_f32 v[132:133], v[36:37], v[228:229], v[132:133] op_sel_hi:[1,0,1]
	v_pk_fma_f32 v[148:149], v[36:37], v[230:231], v[148:149] op_sel_hi:[1,0,1]
	v_pk_fma_f32 v[134:135], v[38:39], v[228:229], v[134:135] op_sel_hi:[1,0,1]
	v_pk_fma_f32 v[150:151], v[38:39], v[230:231], v[150:151] op_sel_hi:[1,0,1]
	s_waitcnt lgkmcnt(5)
	v_pk_fma_f32 v[136:137], v[40:41], v[228:229], v[136:137] op_sel_hi:[1,0,1]
	v_pk_fma_f32 v[152:153], v[40:41], v[230:231], v[152:153] op_sel_hi:[1,0,1]
	v_pk_fma_f32 v[138:139], v[42:43], v[228:229], v[138:139] op_sel_hi:[1,0,1]
	v_pk_fma_f32 v[154:155], v[42:43], v[230:231], v[154:155] op_sel_hi:[1,0,1]
	s_waitcnt lgkmcnt(4)
	v_pk_fma_f32 v[140:141], v[44:45], v[228:229], v[140:141] op_sel_hi:[1,0,1]
	v_pk_fma_f32 v[156:157], v[44:45], v[230:231], v[156:157] op_sel_hi:[1,0,1]
	v_pk_fma_f32 v[142:143], v[46:47], v[228:229], v[142:143] op_sel_hi:[1,0,1]
	v_pk_fma_f32 v[158:159], v[46:47], v[230:231], v[158:159] op_sel_hi:[1,0,1]
	s_waitcnt lgkmcnt(3)
	v_pk_fma_f32 v[160:161], v[48:49], v[228:229], v[160:161] op_sel_hi:[1,0,1]
	v_pk_fma_f32 v[176:177], v[48:49], v[230:231], v[176:177] op_sel_hi:[1,0,1]
	v_pk_fma_f32 v[162:163], v[50:51], v[228:229], v[162:163] op_sel_hi:[1,0,1]
	v_pk_fma_f32 v[178:179], v[50:51], v[230:231], v[178:179] op_sel_hi:[1,0,1]
	s_waitcnt lgkmcnt(2)
	v_pk_fma_f32 v[164:165], v[52:53], v[228:229], v[164:165] op_sel_hi:[1,0,1]
	v_pk_fma_f32 v[180:181], v[52:53], v[230:231], v[180:181] op_sel_hi:[1,0,1]
	v_pk_fma_f32 v[166:167], v[54:55], v[228:229], v[166:167] op_sel_hi:[1,0,1]
	v_pk_fma_f32 v[182:183], v[54:55], v[230:231], v[182:183] op_sel_hi:[1,0,1]
	s_waitcnt lgkmcnt(1)
	v_pk_fma_f32 v[168:169], v[56:57], v[228:229], v[168:169] op_sel_hi:[1,0,1]
	v_pk_fma_f32 v[184:185], v[56:57], v[230:231], v[184:185] op_sel_hi:[1,0,1]
	v_pk_fma_f32 v[170:171], v[58:59], v[228:229], v[170:171] op_sel_hi:[1,0,1]
	v_pk_fma_f32 v[186:187], v[58:59], v[230:231], v[186:187] op_sel_hi:[1,0,1]
	s_waitcnt lgkmcnt(0)
	v_pk_fma_f32 v[172:173], v[60:61], v[228:229], v[172:173] op_sel_hi:[1,0,1]
	v_pk_fma_f32 v[188:189], v[60:61], v[230:231], v[188:189] op_sel_hi:[1,0,1]
	v_pk_fma_f32 v[174:175], v[62:63], v[228:229], v[174:175] op_sel_hi:[1,0,1]
	v_pk_fma_f32 v[190:191], v[62:63], v[230:231], v[190:191] op_sel_hi:[1,0,1]
	global_load_ushort v200, v3, s[4:5] offset:1024
	global_load_ushort v201, v4, s[6:7]
	global_load_ushort v202, v4, s[8:9]
	global_load_ushort v203, v4, s[10:11]
	v_add_u32_e32 v3, 0xc00, v3
	v_add_u32_e32 v4, 0x400, v4
	s_waitcnt vmcnt(12)
; DI float rl(float x, int l) { return __int_as_float(__builtin_amdgcn_readlane(__float_as_int(x), l)); }
; template <bool PASS2>
; DI void rwkv_item(const Params& p, int l, int item, int lane, const bf16_t* rkv, const bf16_t* lo2, float* rwst) {
;     ...
;   for (int t = 0; t < LCR; t++) {
;     Raw rawC = rawB;
;     if (t + 2 < LCR) rawC = load_raw(tok0 + t + 2);
;     Der nxt = cur;
;     if (t + 1 < LCR) nxt = derive(rawB, rpA, kpA);
;     const float rr = cur.rr, wdec = cur.wdec, kf = cur.kf, av = cur.av, bv = cur.bv, v = cur.v, gg = cur.gg;
;     float sa0 = 0.f, sa1 = 0.f, pa0 = 0.f, pa1 = 0.f;
; #pragma unroll
;     for (int j = 0; j < 64; j += 2) {
;       const float a0 = rl(av, j), a1 = rl(av, j + 1);
;       sa0 += S[j] * a0; sa1 += S[j + 1] * a1;
;       if (!PASS2) { pa0 += P[j] * a0; pa1 += P[j + 1] * a1; }
;     }
;     const float sa = sa0 + sa1, pa = pa0 + pa1;
	v_lshlrev_b32_e32 v27, 16, v204
	v_sub_f32_e32 v29, v7, v27
	v_fma_f32 v29, v29, v10, v27
	v_mov_b32_e32 v7, v27
	v_lshlrev_b32_e32 v30, 16, v206
	v_mul_f32_e32 v30, 0xbfb8aa3b, v30
	v_exp_f32_e32 v30, v30
	v_lshlrev_b32_e32 v31, 16, v207
	v_mfma_f32_32x32x2_f32 v[80:95], v16, v19, v[80:95]
	v_mul_f32_e32 v211, v29, v11
	v_add_f32_e32 v212, -1.0, v31
	v_fma_f32 v212, v212, v12, 1.0
	v_mul_f32_e32 v212, v29, v212
	v_mul_f32_e32 v213, v211, v211
	v_mov_b32_e32 v214, 0
	v_lshlrev_b32_e32 v21, 16, v205
	s_nop 1
	v_mfma_f32_32x32x2_f32 v[96:111], v17, v18, v[96:111]
	v_permlane32_swap_b32 v213, v214
	s_nop 0
	v_add_f32_e32 v213, v213, v214
	s_nop 1
	v_add_f32_dpp v213, v213, v213 quad_perm:[1,0,3,2] row_mask:0xf bank_mask:0xf
	s_nop 1
	v_add_f32_dpp v213, v213, v213 quad_perm:[2,3,0,1] row_mask:0xf bank_mask:0xf
	s_nop 1
	v_mfma_f32_32x32x2_f32 v[112:127], v17, v19, v[112:127]
	v_add_f32_dpp v213, v213, v213 row_half_mirror row_mask:0xf bank_mask:0xf
	s_nop 1
	v_add_f32_dpp v213, v213, v213 row_mirror row_mask:0xf bank_mask:0xf
	s_nop 1
	v_add_f32_dpp v213, v213, v213 row_bcast:15 row_mask:0xa bank_mask:0xf
	s_nop 1
	v_readlane_b32 s28, v213, 31
	v_readlane_b32 s31, v213, 63
	s_nop 1
	v_mov_b32_e32 v215, s28
	v_max_f32_e32 v215, 0x179abe15, v215
	v_rsq_f32_e32 v215, v215
	v_mov_b32_e32 v19, v21
	v_mul_f32_e32 v211, v211, v215
	v_mul_f32_e64 v24, -v211, v8
	v_mul_f32_e32 v216, v211, v31
	v_mul_f32_e32 v8, v8, v30
	v_rcp_f32_e32 v217, v8
	s_nop 0
	v_mul_f32_e32 v16, v216, v217
	v_mul_f32_e32 v17, v212, v217
	ds_write_b32 v1, v16 offset:256
	s_nop 1
	v_permlane32_swap_b32 v16, v17
	ds_write_b32 v1, v24
	ds_read_b128 v[32:35], v2 offset:0
	ds_read_b128 v[36:39], v2 offset:32
	ds_read_b128 v[40:43], v2 offset:64
	ds_read_b128 v[44:47], v2 offset:96
	ds_read_b128 v[48:51], v2 offset:128
	ds_read_b128 v[52:55], v2 offset:160
	ds_read_b128 v[56:59], v2 offset:192
	ds_read_b128 v[60:63], v2 offset:224
	s_waitcnt lgkmcnt(7)
	v_pk_mul_f32 v[220:221], v[64:65], v[32:33]
	v_pk_mul_f32 v[224:225], v[128:129], v[32:33]
	v_pk_mul_f32 v[222:223], v[80:81], v[32:33]
	v_pk_mul_f32 v[226:227], v[144:145], v[32:33]
	v_pk_fma_f32 v[220:221], v[66:67], v[34:35], v[220:221]
	v_pk_fma_f32 v[224:225], v[130:131], v[34:35], v[224:225]
	v_pk_fma_f32 v[222:223], v[82:83], v[34:35], v[222:223]
	v_pk_fma_f32 v[226:227], v[146:147], v[34:35], v[226:227]
	s_waitcnt lgkmcnt(6)
	v_pk_fma_f32 v[220:221], v[68:69], v[36:37], v[220:221]
	v_pk_fma_f32 v[224:225], v[132:133], v[36:37], v[224:225]
	v_pk_fma_f32 v[222:223], v[84:85], v[36:37], v[222:223]
	v_pk_fma_f32 v[226:227], v[148:149], v[36:37], v[226:227]
	v_pk_fma_f32 v[220:221], v[70:71], v[38:39], v[220:221]
	v_pk_fma_f32 v[224:225], v[134:135], v[38:39], v[224:225]
	v_pk_fma_f32 v[222:223], v[86:87], v[38:39], v[222:223]
	v_pk_fma_f32 v[226:227], v[150:151], v[38:39], v[226:227]
	s_waitcnt lgkmcnt(5)
	v_pk_fma_f32 v[220:221], v[72:73], v[40:41], v[220:221]
	v_pk_fma_f32 v[224:225], v[136:137], v[40:41], v[224:225]
	v_pk_fma_f32 v[222:223], v[88:89], v[40:41], v[222:223]
	v_pk_fma_f32 v[226:227], v[152:153], v[40:41], v[226:227]
	v_pk_fma_f32 v[220:221], v[74:75], v[42:43], v[220:221]
	v_pk_fma_f32 v[224:225], v[138:139], v[42:43], v[224:225]
	v_pk_fma_f32 v[222:223], v[90:91], v[42:43], v[222:223]
	v_pk_fma_f32 v[226:227], v[154:155], v[42:43], v[226:227]
	s_waitcnt lgkmcnt(4)
	v_pk_fma_f32 v[220:221], v[76:77], v[44:45], v[220:221]
	v_pk_fma_f32 v[224:225], v[140:141], v[44:45], v[224:225]
	v_pk_fma_f32 v[222:223], v[92:93], v[44:45], v[222:223]
	v_pk_fma_f32 v[226:227], v[156:157], v[44:45], v[226:227]
	v_pk_fma_f32 v[220:221], v[78:79], v[46:47], v[220:221]
	v_pk_fma_f32 v[224:225], v[142:143], v[46:47], v[224:225]
	v_pk_fma_f32 v[222:223], v[94:95], v[46:47], v[222:223]
	v_pk_fma_f32 v[226:227], v[158:159], v[46:47], v[226:227]
	s_waitcnt lgkmcnt(3)
	v_pk_fma_f32 v[220:221], v[96:97], v[48:49], v[220:221]
	v_pk_fma_f32 v[224:225], v[160:161], v[48:49], v[224:225]
	v_pk_fma_f32 v[222:223], v[112:113], v[48:49], v[222:223]
	v_pk_fma_f32 v[226:227], v[176:177], v[48:49], v[226:227]
	v_pk_fma_f32 v[220:221], v[98:99], v[50:51], v[220:221]
	v_pk_fma_f32 v[224:225], v[162:163], v[50:51], v[224:225]
	v_pk_fma_f32 v[222:223], v[114:115], v[50:51], v[222:223]
	v_pk_fma_f32 v[226:227], v[178:179], v[50:51], v[226:227]
	s_waitcnt lgkmcnt(2)
	v_pk_fma_f32 v[220:221], v[100:101], v[52:53], v[220:221]
	v_pk_fma_f32 v[224:225], v[164:165], v[52:53], v[224:225]
	v_pk_fma_f32 v[222:223], v[116:117], v[52:53], v[222:223]
	v_pk_fma_f32 v[226:227], v[180:181], v[52:53], v[226:227]
	v_pk_fma_f32 v[220:221], v[102:103], v[54:55], v[220:221]
	v_pk_fma_f32 v[224:225], v[166:167], v[54:55], v[224:225]
	v_pk_fma_f32 v[222:223], v[118:119], v[54:55], v[222:223]
	v_pk_fma_f32 v[226:227], v[182:183], v[54:55], v[226:227]
	s_waitcnt lgkmcnt(1)
	v_pk_fma_f32 v[220:221], v[104:105], v[56:57], v[220:221]
	v_pk_fma_f32 v[224:225], v[168:169], v[56:57], v[224:225]
	v_pk_fma_f32 v[222:223], v[120:121], v[56:57], v[222:223]
	v_pk_fma_f32 v[226:227], v[184:185], v[56:57], v[226:227]
	v_pk_fma_f32 v[220:221], v[106:107], v[58:59], v[220:221]
	v_pk_fma_f32 v[224:225], v[170:171], v[58:59], v[224:225]
	v_pk_fma_f32 v[222:223], v[122:123], v[58:59], v[222:223]
	v_pk_fma_f32 v[226:227], v[186:187], v[58:59], v[226:227]
	s_waitcnt lgkmcnt(0)
; DI float rl(float x, int l) { return __int_as_float(__builtin_amdgcn_readlane(__float_as_int(x), l)); }
; template <bool PASS2>
; DI void rwkv_item(const Params& p, int l, int item, int lane, const bf16_t* rkv, const bf16_t* lo2, float* rwst) {
;     ...
;   for (int t = 0; t < LCR; t++) {
;     Raw rawC = rawB;
;     if (t + 2 < LCR) rawC = load_raw(tok0 + t + 2);
;     Der nxt = cur;
;     if (t + 1 < LCR) nxt = derive(rawB, rpA, kpA);
;     const float rr = cur.rr, wdec = cur.wdec, kf = cur.kf, av = cur.av, bv = cur.bv, v = cur.v, gg = cur.gg;
;     float sa0 = 0.f, sa1 = 0.f, pa0 = 0.f, pa1 = 0.f;
; #pragma unroll
;     for (int j = 0; j < 64; j += 2) {
;       const float a0 = rl(av, j), a1 = rl(av, j + 1);
;       sa0 += S[j] * a0; sa1 += S[j + 1] * a1;
;       if (!PASS2) { pa0 += P[j] * a0; pa1 += P[j + 1] * a1; }
;     }
;     const float sa = sa0 + sa1, pa = pa0 + pa1;
;     float y0 = 0.f, y1 = 0.f;
; #pragma unroll
;     for (int j = 0; j < 64; j += 2) {
;       const float w0 = rl(wdec, j), b0 = rl(bv, j), k0 = rl(kf, j);
;       const float w1 = rl(wdec, j + 1), b1 = rl(bv, j + 1), k1 = rl(kf, j + 1);
;       S[j] = S[j] * w0 + sa * b0 + v * k0;
;       S[j + 1] = S[j + 1] * w1 + sa * b1 + v * k1;
;       if (!PASS2) {
;         P[j] = P[j] * w0 + pa * b0;
;         P[j + 1] = P[j + 1] * w1 + pa * b1;
;       } else {
;         y0 += S[j] * rl(rr, j); y1 += S[j + 1] * rl(rr, j + 1);
;       }
;     }
	v_pk_fma_f32 v[220:221], v[108:109], v[60:61], v[220:221]
	v_pk_fma_f32 v[224:225], v[172:173], v[60:61], v[224:225]
	v_pk_fma_f32 v[222:223], v[124:125], v[60:61], v[222:223]
	v_pk_fma_f32 v[226:227], v[188:189], v[60:61], v[226:227]
	v_pk_fma_f32 v[220:221], v[110:111], v[62:63], v[220:221]
	v_pk_fma_f32 v[224:225], v[174:175], v[62:63], v[224:225]
	v_pk_fma_f32 v[222:223], v[126:127], v[62:63], v[222:223]
	v_pk_fma_f32 v[226:227], v[190:191], v[62:63], v[226:227]
	v_add_f32_e32 v18, v220, v221
	v_add_f32_e32 v208, v222, v223
	s_nop 1
	v_permlane32_swap_b32 v18, v208
	s_nop 0
	v_add_f32_e32 v18, v18, v208
	v_add_f32_e32 v228, v224, v225
	v_add_f32_e32 v230, v226, v227
	v_mov_b32_e32 v229, v228
	v_mov_b32_e32 v231, v230
	s_nop 1
	v_permlane32_swap_b32 v228, v229
	v_permlane32_swap_b32 v230, v231
	v_add_f32_e32 v228, v228, v229
	v_add_f32_e32 v230, v230, v231
	s_nop 1
	v_permlane32_swap_b32 v18, v19
	s_nop 1
	v_mfma_f32_32x32x2_f32 v[64:79], v16, v18, v[64:79]
	ds_read_b128 v[32:35], v2 offset:256
	ds_read_b128 v[36:39], v2 offset:288
	ds_read_b128 v[40:43], v2 offset:320
	ds_read_b128 v[44:47], v2 offset:352
	ds_read_b128 v[48:51], v2 offset:384
	ds_read_b128 v[52:55], v2 offset:416
	ds_read_b128 v[56:59], v2 offset:448
	ds_read_b128 v[60:63], v2 offset:480
	s_waitcnt lgkmcnt(7)
	v_pk_fma_f32 v[128:129], v[32:33], v[228:229], v[128:129] op_sel_hi:[1,0,1]
	v_pk_fma_f32 v[144:145], v[32:33], v[230:231], v[144:145] op_sel_hi:[1,0,1]
	v_pk_fma_f32 v[130:131], v[34:35], v[228:229], v[130:131] op_sel_hi:[1,0,1]
	v_pk_fma_f32 v[146:147], v[34:35], v[230:231], v[146:147] op_sel_hi:[1,0,1]
	s_waitcnt lgkmcnt(6)
	v_pk_fma_f32 v[132:133], v[36:37], v[228:229], v[132:133] op_sel_hi:[1,0,1]
	v_pk_fma_f32 v[148:149], v[36:37], v[230:231], v[148:149] op_sel_hi:[1,0,1]
	v_pk_fma_f32 v[134:135], v[38:39], v[228:229], v[134:135] op_sel_hi:[1,0,1]
	v_pk_fma_f32 v[150:151], v[38:39], v[230:231], v[150:151] op_sel_hi:[1,0,1]
	s_waitcnt lgkmcnt(5)
	v_pk_fma_f32 v[136:137], v[40:41], v[228:229], v[136:137] op_sel_hi:[1,0,1]
	v_pk_fma_f32 v[152:153], v[40:41], v[230:231], v[152:153] op_sel_hi:[1,0,1]
	v_pk_fma_f32 v[138:139], v[42:43], v[228:229], v[138:139] op_sel_hi:[1,0,1]
	v_pk_fma_f32 v[154:155], v[42:43], v[230:231], v[154:155] op_sel_hi:[1,0,1]
	s_waitcnt lgkmcnt(4)
	v_pk_fma_f32 v[140:141], v[44:45], v[228:229], v[140:141] op_sel_hi:[1,0,1]
	v_pk_fma_f32 v[156:157], v[44:45], v[230:231], v[156:157] op_sel_hi:[1,0,1]
	v_pk_fma_f32 v[142:143], v[46:47], v[228:229], v[142:143] op_sel_hi:[1,0,1]
	v_pk_fma_f32 v[158:159], v[46:47], v[230:231], v[158:159] op_sel_hi:[1,0,1]
	s_waitcnt lgkmcnt(3)
	v_pk_fma_f32 v[160:161], v[48:49], v[228:229], v[160:161] op_sel_hi:[1,0,1]
	v_pk_fma_f32 v[176:177], v[48:49], v[230:231], v[176:177] op_sel_hi:[1,0,1]
	v_pk_fma_f32 v[162:163], v[50:51], v[228:229], v[162:163] op_sel_hi:[1,0,1]
	v_pk_fma_f32 v[178:179], v[50:51], v[230:231], v[178:179] op_sel_hi:[1,0,1]
	s_waitcnt lgkmcnt(2)
	v_pk_fma_f32 v[164:165], v[52:53], v[228:229], v[164:165] op_sel_hi:[1,0,1]
	v_pk_fma_f32 v[180:181], v[52:53], v[230:231], v[180:181] op_sel_hi:[1,0,1]
	v_pk_fma_f32 v[166:167], v[54:55], v[228:229], v[166:167] op_sel_hi:[1,0,1]
	v_pk_fma_f32 v[182:183], v[54:55], v[230:231], v[182:183] op_sel_hi:[1,0,1]
	s_waitcnt lgkmcnt(1)
	v_pk_fma_f32 v[168:169], v[56:57], v[228:229], v[168:169] op_sel_hi:[1,0,1]
	v_pk_fma_f32 v[184:185], v[56:57], v[230:231], v[184:185] op_sel_hi:[1,0,1]
	v_pk_fma_f32 v[170:171], v[58:59], v[228:229], v[170:171] op_sel_hi:[1,0,1]
	v_pk_fma_f32 v[186:187], v[58:59], v[230:231], v[186:187] op_sel_hi:[1,0,1]
	s_waitcnt lgkmcnt(0)
	v_pk_fma_f32 v[172:173], v[60:61], v[228:229], v[172:173] op_sel_hi:[1,0,1]
	v_pk_fma_f32 v[188:189], v[60:61], v[230:231], v[188:189] op_sel_hi:[1,0,1]
	v_pk_fma_f32 v[174:175], v[62:63], v[228:229], v[174:175] op_sel_hi:[1,0,1]
	v_pk_fma_f32 v[190:191], v[62:63], v[230:231], v[190:191] op_sel_hi:[1,0,1]
	global_load_ushort v204, v3, s[4:5] offset:1024
	global_load_ushort v205, v4, s[6:7]
	global_load_ushort v206, v4, s[8:9]
	global_load_ushort v207, v4, s[10:11]
	v_add_u32_e32 v3, 0xc00, v3
	v_add_u32_e32 v4, 0x400, v4
	s_waitcnt vmcnt(12)
	v_mov_b32_e32 v218, v8
	v_lshlrev_b32_e32 v27, 16, v192
	v_sub_f32_e32 v29, v7, v27
	v_fma_f32 v29, v29, v10, v27
	v_mov_b32_e32 v7, v27
	v_lshlrev_b32_e32 v30, 16, v194
	v_mul_f32_e32 v30, 0xbfb8aa3b, v30
	v_exp_f32_e32 v30, v30
	v_lshlrev_b32_e32 v31, 16, v195
	v_mfma_f32_32x32x2_f32 v[80:95], v16, v19, v[80:95]
	v_mul_f32_e32 v211, v29, v11
	v_add_f32_e32 v212, -1.0, v31
	v_fma_f32 v212, v212, v12, 1.0
	v_mul_f32_e32 v212, v29, v212
	v_mul_f32_e32 v213, v211, v211
	v_mov_b32_e32 v214, 0
	v_lshlrev_b32_e32 v20, 16, v193
	s_nop 1
	v_mfma_f32_32x32x2_f32 v[96:111], v17, v18, v[96:111]
	v_permlane32_swap_b32 v213, v214
	s_nop 0
	v_add_f32_e32 v213, v213, v214
	s_nop 1
	v_add_f32_dpp v213, v213, v213 quad_perm:[1,0,3,2] row_mask:0xf bank_mask:0xf
	s_nop 1
	v_add_f32_dpp v213, v213, v213 quad_perm:[2,3,0,1] row_mask:0xf bank_mask:0xf
	s_nop 1
	v_mfma_f32_32x32x2_f32 v[112:127], v17, v19, v[112:127]
	v_add_f32_dpp v213, v213, v213 row_half_mirror row_mask:0xf bank_mask:0xf
	s_nop 1
	v_add_f32_dpp v213, v213, v213 row_mirror row_mask:0xf bank_mask:0xf
	s_nop 1
	v_add_f32_dpp v213, v213, v213 row_bcast:15 row_mask:0xa bank_mask:0xf
	s_nop 1
	v_readlane_b32 s28, v213, 31
	v_readlane_b32 s30, v213, 63
	s_nop 1
	v_mov_b32_e32 v215, s28
	v_max_f32_e32 v215, 0x179abe15, v215
	v_rsq_f32_e32 v215, v215
	v_mov_b32_e32 v19, v20
	v_mul_f32_e32 v211, v211, v215
	v_mul_f32_e64 v24, -v211, v8
	v_mul_f32_e32 v216, v211, v31
	v_mul_f32_e32 v8, v8, v30
	v_rcp_f32_e32 v217, v8
	s_nop 0
	v_mul_f32_e32 v16, v216, v217
	v_mul_f32_e32 v17, v212, v217
	ds_write_b32 v1, v16 offset:256
	s_nop 1
	v_permlane32_swap_b32 v16, v17
	ds_write_b32 v1, v24
	ds_read_b128 v[32:35], v2 offset:0
	ds_read_b128 v[36:39], v2 offset:32
	ds_read_b128 v[40:43], v2 offset:64
	ds_read_b128 v[44:47], v2 offset:96
	ds_read_b128 v[48:51], v2 offset:128
	ds_read_b128 v[52:55], v2 offset:160
	ds_read_b128 v[56:59], v2 offset:192
	ds_read_b128 v[60:63], v2 offset:224
	s_waitcnt lgkmcnt(7)
; DI float rl(float x, int l) { return __int_as_float(__builtin_amdgcn_readlane(__float_as_int(x), l)); }
; template <bool PASS2>
; DI void rwkv_item(const Params& p, int l, int item, int lane, const bf16_t* rkv, const bf16_t* lo2, float* rwst) {
;     ...
;   for (int t = 0; t < LCR; t++) {
;     Raw rawC = rawB;
;     if (t + 2 < LCR) rawC = load_raw(tok0 + t + 2);
;     Der nxt = cur;
;     if (t + 1 < LCR) nxt = derive(rawB, rpA, kpA);
;     const float rr = cur.rr, wdec = cur.wdec, kf = cur.kf, av = cur.av, bv = cur.bv, v = cur.v, gg = cur.gg;
;     float sa0 = 0.f, sa1 = 0.f, pa0 = 0.f, pa1 = 0.f;
; #pragma unroll
;     for (int j = 0; j < 64; j += 2) {
;       const float a0 = rl(av, j), a1 = rl(av, j + 1);
;       sa0 += S[j] * a0; sa1 += S[j + 1] * a1;
;       if (!PASS2) { pa0 += P[j] * a0; pa1 += P[j + 1] * a1; }
;     }
;     const float sa = sa0 + sa1, pa = pa0 + pa1;
	v_pk_mul_f32 v[220:221], v[64:65], v[32:33]
	v_pk_mul_f32 v[224:225], v[128:129], v[32:33]
	v_pk_mul_f32 v[222:223], v[80:81], v[32:33]
	v_pk_mul_f32 v[226:227], v[144:145], v[32:33]
	v_pk_fma_f32 v[220:221], v[66:67], v[34:35], v[220:221]
	v_pk_fma_f32 v[224:225], v[130:131], v[34:35], v[224:225]
	v_pk_fma_f32 v[222:223], v[82:83], v[34:35], v[222:223]
	v_pk_fma_f32 v[226:227], v[146:147], v[34:35], v[226:227]
	s_waitcnt lgkmcnt(6)
	v_pk_fma_f32 v[220:221], v[68:69], v[36:37], v[220:221]
	v_pk_fma_f32 v[224:225], v[132:133], v[36:37], v[224:225]
	v_pk_fma_f32 v[222:223], v[84:85], v[36:37], v[222:223]
	v_pk_fma_f32 v[226:227], v[148:149], v[36:37], v[226:227]
	v_pk_fma_f32 v[220:221], v[70:71], v[38:39], v[220:221]
	v_pk_fma_f32 v[224:225], v[134:135], v[38:39], v[224:225]
	v_pk_fma_f32 v[222:223], v[86:87], v[38:39], v[222:223]
	v_pk_fma_f32 v[226:227], v[150:151], v[38:39], v[226:227]
	s_waitcnt lgkmcnt(5)
	v_pk_fma_f32 v[220:221], v[72:73], v[40:41], v[220:221]
	v_pk_fma_f32 v[224:225], v[136:137], v[40:41], v[224:225]
	v_pk_fma_f32 v[222:223], v[88:89], v[40:41], v[222:223]
	v_pk_fma_f32 v[226:227], v[152:153], v[40:41], v[226:227]
	v_pk_fma_f32 v[220:221], v[74:75], v[42:43], v[220:221]
	v_pk_fma_f32 v[224:225], v[138:139], v[42:43], v[224:225]
	v_pk_fma_f32 v[222:223], v[90:91], v[42:43], v[222:223]
	v_pk_fma_f32 v[226:227], v[154:155], v[42:43], v[226:227]
	s_waitcnt lgkmcnt(4)
	v_pk_fma_f32 v[220:221], v[76:77], v[44:45], v[220:221]
	v_pk_fma_f32 v[224:225], v[140:141], v[44:45], v[224:225]
	v_pk_fma_f32 v[222:223], v[92:93], v[44:45], v[222:223]
	v_pk_fma_f32 v[226:227], v[156:157], v[44:45], v[226:227]
	v_pk_fma_f32 v[220:221], v[78:79], v[46:47], v[220:221]
	v_pk_fma_f32 v[224:225], v[142:143], v[46:47], v[224:225]
	v_pk_fma_f32 v[222:223], v[94:95], v[46:47], v[222:223]
	v_pk_fma_f32 v[226:227], v[158:159], v[46:47], v[226:227]
	s_waitcnt lgkmcnt(3)
	v_pk_fma_f32 v[220:221], v[96:97], v[48:49], v[220:221]
	v_pk_fma_f32 v[224:225], v[160:161], v[48:49], v[224:225]
	v_pk_fma_f32 v[222:223], v[112:113], v[48:49], v[222:223]
	v_pk_fma_f32 v[226:227], v[176:177], v[48:49], v[226:227]
	v_pk_fma_f32 v[220:221], v[98:99], v[50:51], v[220:221]
	v_pk_fma_f32 v[224:225], v[162:163], v[50:51], v[224:225]
	v_pk_fma_f32 v[222:223], v[114:115], v[50:51], v[222:223]
	v_pk_fma_f32 v[226:227], v[178:179], v[50:51], v[226:227]
	s_waitcnt lgkmcnt(2)
	v_pk_fma_f32 v[220:221], v[100:101], v[52:53], v[220:221]
	v_pk_fma_f32 v[224:225], v[164:165], v[52:53], v[224:225]
	v_pk_fma_f32 v[222:223], v[116:117], v[52:53], v[222:223]
	v_pk_fma_f32 v[226:227], v[180:181], v[52:53], v[226:227]
	v_pk_fma_f32 v[220:221], v[102:103], v[54:55], v[220:221]
	v_pk_fma_f32 v[224:225], v[166:167], v[54:55], v[224:225]
	v_pk_fma_f32 v[222:223], v[118:119], v[54:55], v[222:223]
	v_pk_fma_f32 v[226:227], v[182:183], v[54:55], v[226:227]
	s_waitcnt lgkmcnt(1)
	v_pk_fma_f32 v[220:221], v[104:105], v[56:57], v[220:221]
	v_pk_fma_f32 v[224:225], v[168:169], v[56:57], v[224:225]
	v_pk_fma_f32 v[222:223], v[120:121], v[56:57], v[222:223]
	v_pk_fma_f32 v[226:227], v[184:185], v[56:57], v[226:227]
	v_pk_fma_f32 v[220:221], v[106:107], v[58:59], v[220:221]
	v_pk_fma_f32 v[224:225], v[170:171], v[58:59], v[224:225]
	v_pk_fma_f32 v[222:223], v[122:123], v[58:59], v[222:223]
	v_pk_fma_f32 v[226:227], v[186:187], v[58:59], v[226:227]
	s_waitcnt lgkmcnt(0)
	v_pk_fma_f32 v[220:221], v[108:109], v[60:61], v[220:221]
	v_pk_fma_f32 v[224:225], v[172:173], v[60:61], v[224:225]
	v_pk_fma_f32 v[222:223], v[124:125], v[60:61], v[222:223]
	v_pk_fma_f32 v[226:227], v[188:189], v[60:61], v[226:227]
	v_pk_fma_f32 v[220:221], v[110:111], v[62:63], v[220:221]
	v_pk_fma_f32 v[224:225], v[174:175], v[62:63], v[224:225]
	v_pk_fma_f32 v[222:223], v[126:127], v[62:63], v[222:223]
	v_pk_fma_f32 v[226:227], v[190:191], v[62:63], v[226:227]
	v_add_f32_e32 v18, v220, v221
	v_add_f32_e32 v208, v222, v223
	s_nop 1
	v_permlane32_swap_b32 v18, v208
	s_nop 0
	v_add_f32_e32 v18, v18, v208
	v_add_f32_e32 v228, v224, v225
	v_add_f32_e32 v230, v226, v227
	v_mov_b32_e32 v229, v228
	v_mov_b32_e32 v231, v230
	s_nop 1
	v_permlane32_swap_b32 v228, v229
	v_permlane32_swap_b32 v230, v231
	v_add_f32_e32 v228, v228, v229
	v_add_f32_e32 v230, v230, v231
	s_add_u32 s18, s18, 4
	s_cmp_lt_u32 s18, 128
	s_cbranch_scc1 .Lrwp1a_loop
; template <bool PASS2>
; DI void rwkv_item(const Params& p, int l, int item, int lane, const bf16_t* rkv, const bf16_t* lo2, float* rwst) {
;     ...
;   if (!PASS2) {
;     float4* sp = (float4*)(stS + lane * 64);
;     float4* pp = (float4*)(stP + lane * 64);
; #pragma unroll
;     for (int j = 0; j < 16; j++) {
;       sp[j] = make_float4(S[4 * j], S[4 * j + 1], S[4 * j + 2], S[4 * j + 3]);
;       pp[j] = make_float4(P[4 * j], P[4 * j + 1], P[4 * j + 2], P[4 * j + 3]);
;     }
;   }
	ds_write_b32 v1, v218
	ds_read_b128 v[32:35], v2 offset:0
	ds_read_b128 v[36:39], v2 offset:32
	ds_read_b128 v[40:43], v2 offset:64
	ds_read_b128 v[44:47], v2 offset:96
	ds_read_b128 v[48:51], v2 offset:128
	ds_read_b128 v[52:55], v2 offset:160
	ds_read_b128 v[56:59], v2 offset:192
	ds_read_b128 v[60:63], v2 offset:224
	s_waitcnt lgkmcnt(0)
	s_nop 7
	s_nop 7
	s_nop 3
	v_pk_mul_f32 v[64:65], v[64:65], v[32:33]
	v_pk_mul_f32 v[128:129], v[128:129], v[32:33]
	v_pk_mul_f32 v[66:67], v[66:67], v[34:35]
	v_pk_mul_f32 v[130:131], v[130:131], v[34:35]
	v_pk_mul_f32 v[68:69], v[68:69], v[36:37]
	v_pk_mul_f32 v[132:133], v[132:133], v[36:37]
	v_pk_mul_f32 v[70:71], v[70:71], v[38:39]
	v_pk_mul_f32 v[134:135], v[134:135], v[38:39]
	v_pk_mul_f32 v[72:73], v[72:73], v[40:41]
	v_pk_mul_f32 v[136:137], v[136:137], v[40:41]
	v_pk_mul_f32 v[74:75], v[74:75], v[42:43]
	v_pk_mul_f32 v[138:139], v[138:139], v[42:43]
	v_pk_mul_f32 v[76:77], v[76:77], v[44:45]
	v_pk_mul_f32 v[140:141], v[140:141], v[44:45]
	v_pk_mul_f32 v[78:79], v[78:79], v[46:47]
	v_pk_mul_f32 v[142:143], v[142:143], v[46:47]
	v_pk_mul_f32 v[80:81], v[80:81], v[32:33]
	v_pk_mul_f32 v[144:145], v[144:145], v[32:33]
	v_pk_mul_f32 v[82:83], v[82:83], v[34:35]
	v_pk_mul_f32 v[146:147], v[146:147], v[34:35]
	v_pk_mul_f32 v[84:85], v[84:85], v[36:37]
	v_pk_mul_f32 v[148:149], v[148:149], v[36:37]
	v_pk_mul_f32 v[86:87], v[86:87], v[38:39]
	v_pk_mul_f32 v[150:151], v[150:151], v[38:39]
	v_pk_mul_f32 v[88:89], v[88:89], v[40:41]
	v_pk_mul_f32 v[152:153], v[152:153], v[40:41]
	v_pk_mul_f32 v[90:91], v[90:91], v[42:43]
	v_pk_mul_f32 v[154:155], v[154:155], v[42:43]
	v_pk_mul_f32 v[92:93], v[92:93], v[44:45]
	v_pk_mul_f32 v[156:157], v[156:157], v[44:45]
	v_pk_mul_f32 v[94:95], v[94:95], v[46:47]
	v_pk_mul_f32 v[158:159], v[158:159], v[46:47]
	v_pk_mul_f32 v[96:97], v[96:97], v[48:49]
	v_pk_mul_f32 v[160:161], v[160:161], v[48:49]
	v_pk_mul_f32 v[98:99], v[98:99], v[50:51]
	v_pk_mul_f32 v[162:163], v[162:163], v[50:51]
	v_pk_mul_f32 v[100:101], v[100:101], v[52:53]
	v_pk_mul_f32 v[164:165], v[164:165], v[52:53]
	v_pk_mul_f32 v[102:103], v[102:103], v[54:55]
	v_pk_mul_f32 v[166:167], v[166:167], v[54:55]
	v_pk_mul_f32 v[104:105], v[104:105], v[56:57]
	v_pk_mul_f32 v[168:169], v[168:169], v[56:57]
	v_pk_mul_f32 v[106:107], v[106:107], v[58:59]
	v_pk_mul_f32 v[170:171], v[170:171], v[58:59]
	v_pk_mul_f32 v[108:109], v[108:109], v[60:61]
	v_pk_mul_f32 v[172:173], v[172:173], v[60:61]
	v_pk_mul_f32 v[110:111], v[110:111], v[62:63]
	v_pk_mul_f32 v[174:175], v[174:175], v[62:63]
	v_pk_mul_f32 v[112:113], v[112:113], v[48:49]
	v_pk_mul_f32 v[176:177], v[176:177], v[48:49]
	v_pk_mul_f32 v[114:115], v[114:115], v[50:51]
	v_pk_mul_f32 v[178:179], v[178:179], v[50:51]
	v_pk_mul_f32 v[116:117], v[116:117], v[52:53]
	v_pk_mul_f32 v[180:181], v[180:181], v[52:53]
	v_pk_mul_f32 v[118:119], v[118:119], v[54:55]
	v_pk_mul_f32 v[182:183], v[182:183], v[54:55]
	v_pk_mul_f32 v[120:121], v[120:121], v[56:57]
	v_pk_mul_f32 v[184:185], v[184:185], v[56:57]
	v_pk_mul_f32 v[122:123], v[122:123], v[58:59]
	v_pk_mul_f32 v[186:187], v[186:187], v[58:59]
	v_pk_mul_f32 v[124:125], v[124:125], v[60:61]
	v_pk_mul_f32 v[188:189], v[188:189], v[60:61]
	v_pk_mul_f32 v[126:127], v[126:127], v[62:63]
	v_pk_mul_f32 v[190:191], v[190:191], v[62:63]
	global_store_dwordx4 v26, v[64:67], s[24:25] offset:0
	global_store_dwordx4 v26, v[128:131], s[40:41] offset:0
	global_store_dwordx4 v26, v[68:71], s[24:25] offset:32
	global_store_dwordx4 v26, v[132:135], s[40:41] offset:32
	global_store_dwordx4 v26, v[72:75], s[24:25] offset:64
	global_store_dwordx4 v26, v[136:139], s[40:41] offset:64
	global_store_dwordx4 v26, v[76:79], s[24:25] offset:96
	global_store_dwordx4 v26, v[140:143], s[40:41] offset:96
	global_store_dwordx4 v26, v[80:83], s[26:27] offset:0
	global_store_dwordx4 v26, v[144:147], s[38:39] offset:0
	global_store_dwordx4 v26, v[84:87], s[26:27] offset:32
	global_store_dwordx4 v26, v[148:151], s[38:39] offset:32
	global_store_dwordx4 v26, v[88:91], s[26:27] offset:64
	global_store_dwordx4 v26, v[152:155], s[38:39] offset:64
	global_store_dwordx4 v26, v[92:95], s[26:27] offset:96
	global_store_dwordx4 v26, v[156:159], s[38:39] offset:96
	global_store_dwordx4 v26, v[96:99], s[24:25] offset:128
	global_store_dwordx4 v26, v[160:163], s[40:41] offset:128
	global_store_dwordx4 v26, v[100:103], s[24:25] offset:160
	global_store_dwordx4 v26, v[164:167], s[40:41] offset:160
	global_store_dwordx4 v26, v[104:107], s[24:25] offset:192
	global_store_dwordx4 v26, v[168:171], s[40:41] offset:192
	global_store_dwordx4 v26, v[108:111], s[24:25] offset:224
	global_store_dwordx4 v26, v[172:175], s[40:41] offset:224
	global_store_dwordx4 v26, v[112:115], s[26:27] offset:128
	global_store_dwordx4 v26, v[176:179], s[38:39] offset:128
	global_store_dwordx4 v26, v[116:119], s[26:27] offset:160
	global_store_dwordx4 v26, v[180:183], s[38:39] offset:160
	global_store_dwordx4 v26, v[120:123], s[26:27] offset:192
	global_store_dwordx4 v26, v[184:187], s[38:39] offset:192
	global_store_dwordx4 v26, v[124:127], s[26:27] offset:224
	global_store_dwordx4 v26, v[188:191], s[38:39] offset:224
	s_waitcnt vmcnt(0)
	s_add_u32 s16, s16, s17
	s_cmpk_lt_i32 s16, 0x800
	s_cbranch_scc1 .Lrwp1a_item
